# speedup vs baseline: 1.0153x; 1.0153x over previous
.LBB0_260:
	s_andn2_b64 vcc, exec, s[46:47]
	s_cbranch_vccnz .LBB0_254
	v_add_co_u32_e32 v248, vcc, 0x800, v130
	s_nop 1
	v_addc_co_u32_e32 v249, vcc, 0, v131, vcc
	global_load_dwordx2 v[132:133], v[248:249], off offset:-2048
	global_load_dwordx2 v[134:135], v[248:249], off offset:2048
	global_load_dwordx2 v[136:137], v[248:249], off offset:-2016
	global_load_dwordx2 v[138:139], v[248:249], off offset:2080
	global_load_dwordx2 v[140:141], v[248:249], off offset:-1792
	global_load_dwordx2 v[142:143], v[248:249], off offset:2304
	global_load_dwordx2 v[144:145], v[248:249], off offset:-1760
	global_load_dwordx2 v[146:147], v[248:249], off offset:2336
	v_add_co_u32_e32 v250, vcc, 0x6c800, v130
	s_nop 1
	v_addc_co_u32_e32 v251, vcc, 0, v131, vcc
	global_load_dwordx2 v[148:149], v[250:251], off offset:-2048
	global_load_dwordx2 v[150:151], v[250:251], off offset:2048
	global_load_dwordx2 v[152:153], v[250:251], off offset:-2016
	global_load_dwordx2 v[154:155], v[250:251], off offset:2080
	global_load_dwordx2 v[156:157], v[250:251], off offset:-1792
	global_load_dwordx2 v[158:159], v[250:251], off offset:2304
	global_load_dwordx2 v[160:161], v[250:251], off offset:-1760
	global_load_dwordx2 v[162:163], v[250:251], off offset:2336
	v_add_co_u32_e32 v248, vcc, 0xd8800, v130
	s_nop 1
	v_addc_co_u32_e32 v249, vcc, 0, v131, vcc
	global_load_dwordx2 v[164:165], v[248:249], off offset:-2048
	global_load_dwordx2 v[166:167], v[248:249], off offset:2048
	global_load_dwordx2 v[168:169], v[248:249], off offset:-2016
	global_load_dwordx2 v[170:171], v[248:249], off offset:2080
	global_load_dwordx2 v[172:173], v[248:249], off offset:-1792
	global_load_dwordx2 v[174:175], v[248:249], off offset:2304
	global_load_dwordx2 v[176:177], v[248:249], off offset:-1760
	global_load_dwordx2 v[178:179], v[248:249], off offset:2336
	v_add_co_u32_e32 v250, vcc, 0x144800, v130
	s_nop 1
	v_addc_co_u32_e32 v251, vcc, 0, v131, vcc
	global_load_dwordx2 v[180:181], v[250:251], off offset:-2048
	global_load_dwordx2 v[182:183], v[250:251], off offset:2048
	global_load_dwordx2 v[184:185], v[250:251], off offset:-2016
	global_load_dwordx2 v[186:187], v[250:251], off offset:2080
	global_load_dwordx2 v[188:189], v[250:251], off offset:-1792
	global_load_dwordx2 v[198:199], v[250:251], off offset:2304
	global_load_dwordx2 v[200:201], v[250:251], off offset:-1760
	global_load_dwordx2 v[202:203], v[250:251], off offset:2336
	s_waitcnt vmcnt(30)
	v_lshlrev_b32_e32 v248, 16, v134
	v_and_b32_e32 v134, 0xffff0000, v134
	v_lshlrev_b32_e32 v249, 16, v135
	v_and_b32_e32 v135, 0xffff0000, v135
	v_max_f32_e32 v248, 0xda24260, v248
	v_max_f32_e32 v134, 0xda24260, v134
	v_max_f32_e32 v249, 0xda24260, v249
	v_max_f32_e32 v135, 0xda24260, v135
	v_rcp_f32_e32 v250, v248
	v_rcp_f32_e32 v251, v134
	v_rcp_f32_e32 v252, v249
	v_rcp_f32_e32 v253, v135
	v_fma_f32 v248, -v248, v250, 1.0
	v_fma_f32 v134, -v134, v251, 1.0
	v_fma_f32 v249, -v249, v252, 1.0
	v_fma_f32 v135, -v135, v253, 1.0
	v_fmac_f32_e32 v250, v248, v250
	v_fmac_f32_e32 v251, v134, v251
	v_fmac_f32_e32 v252, v249, v252
	v_fmac_f32_e32 v253, v135, v253
	v_lshlrev_b32_e32 v248, 16, v132
	v_and_b32_e32 v132, 0xffff0000, v132
	v_lshlrev_b32_e32 v249, 16, v133
	v_and_b32_e32 v133, 0xffff0000, v133
	v_mul_f32_e32 v250, v248, v250
	v_mul_f32_e32 v251, v132, v251
	v_mul_f32_e32 v252, v249, v252
	v_mul_f32_e32 v253, v133, v253
	v_mul_f32_e32 v126, v126, v250
	v_mul_f32_e32 v127, v127, v251
	v_mul_f32_e32 v128, v128, v252
	v_mul_f32_e32 v129, v129, v253
	s_waitcnt vmcnt(28)
	v_lshlrev_b32_e32 v248, 16, v138
	v_and_b32_e32 v138, 0xffff0000, v138
	v_lshlrev_b32_e32 v249, 16, v139
	v_and_b32_e32 v139, 0xffff0000, v139
	v_max_f32_e32 v248, 0xda24260, v248
	v_max_f32_e32 v138, 0xda24260, v138
	v_max_f32_e32 v249, 0xda24260, v249
	v_max_f32_e32 v139, 0xda24260, v139
	v_rcp_f32_e32 v250, v248
	v_rcp_f32_e32 v251, v138
	v_rcp_f32_e32 v252, v249
	v_rcp_f32_e32 v253, v139
	v_fma_f32 v248, -v248, v250, 1.0
	v_fma_f32 v138, -v138, v251, 1.0
	v_fma_f32 v249, -v249, v252, 1.0
	v_fma_f32 v139, -v139, v253, 1.0
	v_fmac_f32_e32 v250, v248, v250
	v_fmac_f32_e32 v251, v138, v251
	v_fmac_f32_e32 v252, v249, v252
	v_fmac_f32_e32 v253, v139, v253
	v_lshlrev_b32_e32 v248, 16, v136
	v_and_b32_e32 v136, 0xffff0000, v136
	v_lshlrev_b32_e32 v249, 16, v137
	v_and_b32_e32 v137, 0xffff0000, v137
	v_mul_f32_e32 v250, v248, v250
	v_mul_f32_e32 v251, v136, v251
	v_mul_f32_e32 v252, v249, v252
	v_mul_f32_e32 v253, v137, v253
	v_mul_f32_e32 v122, v122, v250
	v_mul_f32_e32 v123, v123, v251
	v_mul_f32_e32 v124, v124, v252
	v_mul_f32_e32 v125, v125, v253
	s_waitcnt vmcnt(26)
	v_lshlrev_b32_e32 v248, 16, v142
	v_and_b32_e32 v142, 0xffff0000, v142
	v_lshlrev_b32_e32 v249, 16, v143
	v_and_b32_e32 v143, 0xffff0000, v143
	v_max_f32_e32 v248, 0xda24260, v248
	v_max_f32_e32 v142, 0xda24260, v142
	v_max_f32_e32 v249, 0xda24260, v249
	v_max_f32_e32 v143, 0xda24260, v143
	v_rcp_f32_e32 v250, v248
	v_rcp_f32_e32 v251, v142
	v_rcp_f32_e32 v252, v249
	v_rcp_f32_e32 v253, v143
	v_fma_f32 v248, -v248, v250, 1.0
	v_fma_f32 v142, -v142, v251, 1.0
	v_fma_f32 v249, -v249, v252, 1.0
	v_fma_f32 v143, -v143, v253, 1.0
	v_fmac_f32_e32 v250, v248, v250
	v_fmac_f32_e32 v251, v142, v251
	v_fmac_f32_e32 v252, v249, v252
	v_fmac_f32_e32 v253, v143, v253
	v_lshlrev_b32_e32 v248, 16, v140
	v_and_b32_e32 v140, 0xffff0000, v140
	v_lshlrev_b32_e32 v249, 16, v141
	v_and_b32_e32 v141, 0xffff0000, v141
	v_mul_f32_e32 v250, v248, v250
	v_mul_f32_e32 v251, v140, v251
	v_mul_f32_e32 v252, v249, v252
	v_mul_f32_e32 v253, v141, v253
	v_mul_f32_e32 v94, v94, v250
	v_mul_f32_e32 v95, v95, v251
	v_mul_f32_e32 v96, v96, v252
	v_mul_f32_e32 v97, v97, v253
	s_waitcnt vmcnt(24)
	v_lshlrev_b32_e32 v248, 16, v146
	v_and_b32_e32 v146, 0xffff0000, v146
	v_lshlrev_b32_e32 v249, 16, v147
	v_and_b32_e32 v147, 0xffff0000, v147
	v_max_f32_e32 v248, 0xda24260, v248
	v_max_f32_e32 v146, 0xda24260, v146
	v_max_f32_e32 v249, 0xda24260, v249
	v_max_f32_e32 v147, 0xda24260, v147
	v_rcp_f32_e32 v250, v248
	v_rcp_f32_e32 v251, v146
	v_rcp_f32_e32 v252, v249
	v_rcp_f32_e32 v253, v147
	v_fma_f32 v248, -v248, v250, 1.0
	v_fma_f32 v146, -v146, v251, 1.0
	v_fma_f32 v249, -v249, v252, 1.0
	v_fma_f32 v147, -v147, v253, 1.0
	v_fmac_f32_e32 v250, v248, v250
	v_fmac_f32_e32 v251, v146, v251
	v_fmac_f32_e32 v252, v249, v252
	v_fmac_f32_e32 v253, v147, v253
	v_lshlrev_b32_e32 v248, 16, v144
	v_and_b32_e32 v144, 0xffff0000, v144
	v_lshlrev_b32_e32 v249, 16, v145
	v_and_b32_e32 v145, 0xffff0000, v145
	v_mul_f32_e32 v250, v248, v250
	v_mul_f32_e32 v251, v144, v251
	v_mul_f32_e32 v252, v249, v252
	v_mul_f32_e32 v253, v145, v253
	v_mul_f32_e32 v90, v90, v250
	v_mul_f32_e32 v91, v91, v251
	v_mul_f32_e32 v92, v92, v252
	v_mul_f32_e32 v93, v93, v253
	s_waitcnt vmcnt(22)
	v_lshlrev_b32_e32 v248, 16, v150
	v_and_b32_e32 v150, 0xffff0000, v150
	v_lshlrev_b32_e32 v249, 16, v151
	v_and_b32_e32 v151, 0xffff0000, v151
	v_max_f32_e32 v248, 0xda24260, v248
	v_max_f32_e32 v150, 0xda24260, v150
	v_max_f32_e32 v249, 0xda24260, v249
	v_max_f32_e32 v151, 0xda24260, v151
	v_rcp_f32_e32 v250, v248
	v_rcp_f32_e32 v251, v150
	v_rcp_f32_e32 v252, v249
	v_rcp_f32_e32 v253, v151
	v_fma_f32 v248, -v248, v250, 1.0
	v_fma_f32 v150, -v150, v251, 1.0
	v_fma_f32 v249, -v249, v252, 1.0
	v_fma_f32 v151, -v151, v253, 1.0
	v_fmac_f32_e32 v250, v248, v250
	v_fmac_f32_e32 v251, v150, v251
	v_fmac_f32_e32 v252, v249, v252
	v_fmac_f32_e32 v253, v151, v253
	v_lshlrev_b32_e32 v248, 16, v148
	v_and_b32_e32 v148, 0xffff0000, v148
	v_lshlrev_b32_e32 v249, 16, v149
	v_and_b32_e32 v149, 0xffff0000, v149
	v_mul_f32_e32 v250, v248, v250
	v_mul_f32_e32 v251, v148, v251
	v_mul_f32_e32 v252, v249, v252
	v_mul_f32_e32 v253, v149, v253
	v_mul_f32_e32 v118, v118, v250
	v_mul_f32_e32 v119, v119, v251
	v_mul_f32_e32 v120, v120, v252
	v_mul_f32_e32 v121, v121, v253
	s_waitcnt vmcnt(20)
	v_lshlrev_b32_e32 v248, 16, v154
	v_and_b32_e32 v154, 0xffff0000, v154
	v_lshlrev_b32_e32 v249, 16, v155
	v_and_b32_e32 v155, 0xffff0000, v155
	v_max_f32_e32 v248, 0xda24260, v248
	v_max_f32_e32 v154, 0xda24260, v154
	v_max_f32_e32 v249, 0xda24260, v249
	v_max_f32_e32 v155, 0xda24260, v155
	v_rcp_f32_e32 v250, v248
	v_rcp_f32_e32 v251, v154
	v_rcp_f32_e32 v252, v249
	v_rcp_f32_e32 v253, v155
	v_fma_f32 v248, -v248, v250, 1.0
	v_fma_f32 v154, -v154, v251, 1.0
	v_fma_f32 v249, -v249, v252, 1.0
	v_fma_f32 v155, -v155, v253, 1.0
	v_fmac_f32_e32 v250, v248, v250
	v_fmac_f32_e32 v251, v154, v251
	v_fmac_f32_e32 v252, v249, v252
	v_fmac_f32_e32 v253, v155, v253
	v_lshlrev_b32_e32 v248, 16, v152
	v_and_b32_e32 v152, 0xffff0000, v152
	v_lshlrev_b32_e32 v249, 16, v153
	v_and_b32_e32 v153, 0xffff0000, v153
	v_mul_f32_e32 v250, v248, v250
	v_mul_f32_e32 v251, v152, v251
	v_mul_f32_e32 v252, v249, v252
	v_mul_f32_e32 v253, v153, v253
	v_mul_f32_e32 v114, v114, v250
	v_mul_f32_e32 v115, v115, v251
	v_mul_f32_e32 v116, v116, v252
	v_mul_f32_e32 v117, v117, v253
	s_waitcnt vmcnt(18)
	v_lshlrev_b32_e32 v248, 16, v158
	v_and_b32_e32 v158, 0xffff0000, v158
	v_lshlrev_b32_e32 v249, 16, v159
	v_and_b32_e32 v159, 0xffff0000, v159
	v_max_f32_e32 v248, 0xda24260, v248
	v_max_f32_e32 v158, 0xda24260, v158
	v_max_f32_e32 v249, 0xda24260, v249
	v_max_f32_e32 v159, 0xda24260, v159
	v_rcp_f32_e32 v250, v248
	v_rcp_f32_e32 v251, v158
	v_rcp_f32_e32 v252, v249
	v_rcp_f32_e32 v253, v159
	v_fma_f32 v248, -v248, v250, 1.0
	v_fma_f32 v158, -v158, v251, 1.0
	v_fma_f32 v249, -v249, v252, 1.0
	v_fma_f32 v159, -v159, v253, 1.0
	v_fmac_f32_e32 v250, v248, v250
	v_fmac_f32_e32 v251, v158, v251
	v_fmac_f32_e32 v252, v249, v252
	v_fmac_f32_e32 v253, v159, v253
	v_lshlrev_b32_e32 v248, 16, v156
	v_and_b32_e32 v156, 0xffff0000, v156
	v_lshlrev_b32_e32 v249, 16, v157
	v_and_b32_e32 v157, 0xffff0000, v157
	v_mul_f32_e32 v250, v248, v250
	v_mul_f32_e32 v251, v156, v251
	v_mul_f32_e32 v252, v249, v252
	v_mul_f32_e32 v253, v157, v253
	v_mul_f32_e32 v86, v86, v250
	v_mul_f32_e32 v87, v87, v251
	v_mul_f32_e32 v88, v88, v252
	v_mul_f32_e32 v89, v89, v253
	s_waitcnt vmcnt(16)
	v_lshlrev_b32_e32 v248, 16, v162
	v_and_b32_e32 v162, 0xffff0000, v162
	v_lshlrev_b32_e32 v249, 16, v163
	v_and_b32_e32 v163, 0xffff0000, v163
	v_max_f32_e32 v248, 0xda24260, v248
	v_max_f32_e32 v162, 0xda24260, v162
	v_max_f32_e32 v249, 0xda24260, v249
	v_max_f32_e32 v163, 0xda24260, v163
	v_rcp_f32_e32 v250, v248
	v_rcp_f32_e32 v251, v162
	v_rcp_f32_e32 v252, v249
	v_rcp_f32_e32 v253, v163
	v_fma_f32 v248, -v248, v250, 1.0
	v_fma_f32 v162, -v162, v251, 1.0
	v_fma_f32 v249, -v249, v252, 1.0
	v_fma_f32 v163, -v163, v253, 1.0
	v_fmac_f32_e32 v250, v248, v250
	v_fmac_f32_e32 v251, v162, v251
	v_fmac_f32_e32 v252, v249, v252
	v_fmac_f32_e32 v253, v163, v253
	v_lshlrev_b32_e32 v248, 16, v160
	v_and_b32_e32 v160, 0xffff0000, v160
	v_lshlrev_b32_e32 v249, 16, v161
	v_and_b32_e32 v161, 0xffff0000, v161
	v_mul_f32_e32 v250, v248, v250
	v_mul_f32_e32 v251, v160, v251
	v_mul_f32_e32 v252, v249, v252
	v_mul_f32_e32 v253, v161, v253
	v_mul_f32_e32 v82, v82, v250
	v_mul_f32_e32 v83, v83, v251
	v_mul_f32_e32 v84, v84, v252
	v_mul_f32_e32 v85, v85, v253
	s_waitcnt vmcnt(14)
	v_lshlrev_b32_e32 v248, 16, v166
	v_and_b32_e32 v166, 0xffff0000, v166
	v_lshlrev_b32_e32 v249, 16, v167
	v_and_b32_e32 v167, 0xffff0000, v167
	v_max_f32_e32 v248, 0xda24260, v248
	v_max_f32_e32 v166, 0xda24260, v166
	v_max_f32_e32 v249, 0xda24260, v249
	v_max_f32_e32 v167, 0xda24260, v167
	v_rcp_f32_e32 v250, v248
	v_rcp_f32_e32 v251, v166
	v_rcp_f32_e32 v252, v249
	v_rcp_f32_e32 v253, v167
	v_fma_f32 v248, -v248, v250, 1.0
	v_fma_f32 v166, -v166, v251, 1.0
	v_fma_f32 v249, -v249, v252, 1.0
	v_fma_f32 v167, -v167, v253, 1.0
	v_fmac_f32_e32 v250, v248, v250
	v_fmac_f32_e32 v251, v166, v251
	v_fmac_f32_e32 v252, v249, v252
	v_fmac_f32_e32 v253, v167, v253
	v_lshlrev_b32_e32 v248, 16, v164
	v_and_b32_e32 v164, 0xffff0000, v164
	v_lshlrev_b32_e32 v249, 16, v165
	v_and_b32_e32 v165, 0xffff0000, v165
	v_mul_f32_e32 v250, v248, v250
	v_mul_f32_e32 v251, v164, v251
	v_mul_f32_e32 v252, v249, v252
	v_mul_f32_e32 v253, v165, v253
	v_mul_f32_e32 v110, v110, v250
	v_mul_f32_e32 v111, v111, v251
	v_mul_f32_e32 v112, v112, v252
	v_mul_f32_e32 v113, v113, v253
	s_waitcnt vmcnt(12)
	v_lshlrev_b32_e32 v248, 16, v170
	v_and_b32_e32 v170, 0xffff0000, v170
	v_lshlrev_b32_e32 v249, 16, v171
	v_and_b32_e32 v171, 0xffff0000, v171
	v_max_f32_e32 v248, 0xda24260, v248
	v_max_f32_e32 v170, 0xda24260, v170
	v_max_f32_e32 v249, 0xda24260, v249
	v_max_f32_e32 v171, 0xda24260, v171
	v_rcp_f32_e32 v250, v248
	v_rcp_f32_e32 v251, v170
	v_rcp_f32_e32 v252, v249
	v_rcp_f32_e32 v253, v171
	v_fma_f32 v248, -v248, v250, 1.0
	v_fma_f32 v170, -v170, v251, 1.0
	v_fma_f32 v249, -v249, v252, 1.0
	v_fma_f32 v171, -v171, v253, 1.0
	v_fmac_f32_e32 v250, v248, v250
	v_fmac_f32_e32 v251, v170, v251
	v_fmac_f32_e32 v252, v249, v252
	v_fmac_f32_e32 v253, v171, v253
	v_lshlrev_b32_e32 v248, 16, v168
	v_and_b32_e32 v168, 0xffff0000, v168
	v_lshlrev_b32_e32 v249, 16, v169
	v_and_b32_e32 v169, 0xffff0000, v169
	v_mul_f32_e32 v250, v248, v250
	v_mul_f32_e32 v251, v168, v251
	v_mul_f32_e32 v252, v249, v252
	v_mul_f32_e32 v253, v169, v253
	v_mul_f32_e32 v106, v106, v250
	v_mul_f32_e32 v107, v107, v251
	v_mul_f32_e32 v108, v108, v252
	v_mul_f32_e32 v109, v109, v253
	s_waitcnt vmcnt(10)
	v_lshlrev_b32_e32 v248, 16, v174
	v_and_b32_e32 v174, 0xffff0000, v174
	v_lshlrev_b32_e32 v249, 16, v175
	v_and_b32_e32 v175, 0xffff0000, v175
	v_max_f32_e32 v248, 0xda24260, v248
	v_max_f32_e32 v174, 0xda24260, v174
	v_max_f32_e32 v249, 0xda24260, v249
	v_max_f32_e32 v175, 0xda24260, v175
	v_rcp_f32_e32 v250, v248
	v_rcp_f32_e32 v251, v174
	v_rcp_f32_e32 v252, v249
	v_rcp_f32_e32 v253, v175
	v_fma_f32 v248, -v248, v250, 1.0
	v_fma_f32 v174, -v174, v251, 1.0
	v_fma_f32 v249, -v249, v252, 1.0
	v_fma_f32 v175, -v175, v253, 1.0
	v_fmac_f32_e32 v250, v248, v250
	v_fmac_f32_e32 v251, v174, v251
	v_fmac_f32_e32 v252, v249, v252
	v_fmac_f32_e32 v253, v175, v253
	v_lshlrev_b32_e32 v248, 16, v172
	v_and_b32_e32 v172, 0xffff0000, v172
	v_lshlrev_b32_e32 v249, 16, v173
	v_and_b32_e32 v173, 0xffff0000, v173
	v_mul_f32_e32 v250, v248, v250
	v_mul_f32_e32 v251, v172, v251
	v_mul_f32_e32 v252, v249, v252
	v_mul_f32_e32 v253, v173, v253
	v_mul_f32_e32 v78, v78, v250
	v_mul_f32_e32 v79, v79, v251
	v_mul_f32_e32 v80, v80, v252
	v_mul_f32_e32 v81, v81, v253
	s_waitcnt vmcnt(8)
	v_lshlrev_b32_e32 v248, 16, v178
	v_and_b32_e32 v178, 0xffff0000, v178
	v_lshlrev_b32_e32 v249, 16, v179
	v_and_b32_e32 v179, 0xffff0000, v179
	v_max_f32_e32 v248, 0xda24260, v248
	v_max_f32_e32 v178, 0xda24260, v178
	v_max_f32_e32 v249, 0xda24260, v249
	v_max_f32_e32 v179, 0xda24260, v179
	v_rcp_f32_e32 v250, v248
	v_rcp_f32_e32 v251, v178
	v_rcp_f32_e32 v252, v249
	v_rcp_f32_e32 v253, v179
	v_fma_f32 v248, -v248, v250, 1.0
	v_fma_f32 v178, -v178, v251, 1.0
	v_fma_f32 v249, -v249, v252, 1.0
	v_fma_f32 v179, -v179, v253, 1.0
	v_fmac_f32_e32 v250, v248, v250
	v_fmac_f32_e32 v251, v178, v251
	v_fmac_f32_e32 v252, v249, v252
	v_fmac_f32_e32 v253, v179, v253
	v_lshlrev_b32_e32 v248, 16, v176
	v_and_b32_e32 v176, 0xffff0000, v176
	v_lshlrev_b32_e32 v249, 16, v177
	v_and_b32_e32 v177, 0xffff0000, v177
	v_mul_f32_e32 v250, v248, v250
	v_mul_f32_e32 v251, v176, v251
	v_mul_f32_e32 v252, v249, v252
	v_mul_f32_e32 v253, v177, v253
	v_mul_f32_e32 v74, v74, v250
	v_mul_f32_e32 v75, v75, v251
	v_mul_f32_e32 v76, v76, v252
	v_mul_f32_e32 v77, v77, v253
	s_waitcnt vmcnt(6)
	v_lshlrev_b32_e32 v248, 16, v182
	v_and_b32_e32 v182, 0xffff0000, v182
	v_lshlrev_b32_e32 v249, 16, v183
	v_and_b32_e32 v183, 0xffff0000, v183
	v_max_f32_e32 v248, 0xda24260, v248
	v_max_f32_e32 v182, 0xda24260, v182
	v_max_f32_e32 v249, 0xda24260, v249
	v_max_f32_e32 v183, 0xda24260, v183
	v_rcp_f32_e32 v250, v248
	v_rcp_f32_e32 v251, v182
	v_rcp_f32_e32 v252, v249
	v_rcp_f32_e32 v253, v183
	v_fma_f32 v248, -v248, v250, 1.0
	v_fma_f32 v182, -v182, v251, 1.0
	v_fma_f32 v249, -v249, v252, 1.0
	v_fma_f32 v183, -v183, v253, 1.0
	v_fmac_f32_e32 v250, v248, v250
	v_fmac_f32_e32 v251, v182, v251
	v_fmac_f32_e32 v252, v249, v252
	v_fmac_f32_e32 v253, v183, v253
	v_lshlrev_b32_e32 v248, 16, v180
	v_and_b32_e32 v180, 0xffff0000, v180
	v_lshlrev_b32_e32 v249, 16, v181
	v_and_b32_e32 v181, 0xffff0000, v181
	v_mul_f32_e32 v250, v248, v250
	v_mul_f32_e32 v251, v180, v251
	v_mul_f32_e32 v252, v249, v252
	v_mul_f32_e32 v253, v181, v253
	v_mul_f32_e32 v102, v102, v250
	v_mul_f32_e32 v103, v103, v251
	v_mul_f32_e32 v104, v104, v252
	v_mul_f32_e32 v105, v105, v253
	s_waitcnt vmcnt(4)
	v_lshlrev_b32_e32 v248, 16, v186
	v_and_b32_e32 v186, 0xffff0000, v186
	v_lshlrev_b32_e32 v249, 16, v187
	v_and_b32_e32 v187, 0xffff0000, v187
	v_max_f32_e32 v248, 0xda24260, v248
	v_max_f32_e32 v186, 0xda24260, v186
	v_max_f32_e32 v249, 0xda24260, v249
	v_max_f32_e32 v187, 0xda24260, v187
	v_rcp_f32_e32 v250, v248
	v_rcp_f32_e32 v251, v186
	v_rcp_f32_e32 v252, v249
	v_rcp_f32_e32 v253, v187
	v_fma_f32 v248, -v248, v250, 1.0
	v_fma_f32 v186, -v186, v251, 1.0
	v_fma_f32 v249, -v249, v252, 1.0
	v_fma_f32 v187, -v187, v253, 1.0
	v_fmac_f32_e32 v250, v248, v250
	v_fmac_f32_e32 v251, v186, v251
	v_fmac_f32_e32 v252, v249, v252
	v_fmac_f32_e32 v253, v187, v253
	v_lshlrev_b32_e32 v248, 16, v184
	v_and_b32_e32 v184, 0xffff0000, v184
	v_lshlrev_b32_e32 v249, 16, v185
	v_and_b32_e32 v185, 0xffff0000, v185
	v_mul_f32_e32 v250, v248, v250
	v_mul_f32_e32 v251, v184, v251
	v_mul_f32_e32 v252, v249, v252
	v_mul_f32_e32 v253, v185, v253
	v_mul_f32_e32 v98, v98, v250
	v_mul_f32_e32 v99, v99, v251
	v_mul_f32_e32 v100, v100, v252
	v_mul_f32_e32 v101, v101, v253
	s_waitcnt vmcnt(2)
	v_lshlrev_b32_e32 v248, 16, v198
	v_and_b32_e32 v198, 0xffff0000, v198
	v_lshlrev_b32_e32 v249, 16, v199
	v_and_b32_e32 v199, 0xffff0000, v199
	v_max_f32_e32 v248, 0xda24260, v248
	v_max_f32_e32 v198, 0xda24260, v198
	v_max_f32_e32 v249, 0xda24260, v249
	v_max_f32_e32 v199, 0xda24260, v199
	v_rcp_f32_e32 v250, v248
	v_rcp_f32_e32 v251, v198
	v_rcp_f32_e32 v252, v249
	v_rcp_f32_e32 v253, v199
	v_fma_f32 v248, -v248, v250, 1.0
	v_fma_f32 v198, -v198, v251, 1.0
	v_fma_f32 v249, -v249, v252, 1.0
	v_fma_f32 v199, -v199, v253, 1.0
	v_fmac_f32_e32 v250, v248, v250
	v_fmac_f32_e32 v251, v198, v251
	v_fmac_f32_e32 v252, v249, v252
	v_fmac_f32_e32 v253, v199, v253
	v_lshlrev_b32_e32 v248, 16, v188
	v_and_b32_e32 v188, 0xffff0000, v188
	v_lshlrev_b32_e32 v249, 16, v189
	v_and_b32_e32 v189, 0xffff0000, v189
	v_mul_f32_e32 v250, v248, v250
	v_mul_f32_e32 v251, v188, v251
	v_mul_f32_e32 v252, v249, v252
	v_mul_f32_e32 v253, v189, v253
	v_mul_f32_e32 v70, v70, v250
	v_mul_f32_e32 v71, v71, v251
	v_mul_f32_e32 v72, v72, v252
	v_mul_f32_e32 v73, v73, v253
	s_waitcnt vmcnt(0)
	v_lshlrev_b32_e32 v248, 16, v202
	v_and_b32_e32 v202, 0xffff0000, v202
	v_lshlrev_b32_e32 v249, 16, v203
	v_and_b32_e32 v203, 0xffff0000, v203
	v_max_f32_e32 v248, 0xda24260, v248
	v_max_f32_e32 v202, 0xda24260, v202
	v_max_f32_e32 v249, 0xda24260, v249
	v_max_f32_e32 v203, 0xda24260, v203
	v_rcp_f32_e32 v250, v248
	v_rcp_f32_e32 v251, v202
	v_rcp_f32_e32 v252, v249
	v_rcp_f32_e32 v253, v203
	v_fma_f32 v248, -v248, v250, 1.0
	v_fma_f32 v202, -v202, v251, 1.0
	v_fma_f32 v249, -v249, v252, 1.0
	v_fma_f32 v203, -v203, v253, 1.0
	v_fmac_f32_e32 v250, v248, v250
	v_fmac_f32_e32 v251, v202, v251
	v_fmac_f32_e32 v252, v249, v252
	v_fmac_f32_e32 v253, v203, v253
	v_lshlrev_b32_e32 v248, 16, v200
	v_and_b32_e32 v200, 0xffff0000, v200
	v_lshlrev_b32_e32 v249, 16, v201
	v_and_b32_e32 v201, 0xffff0000, v201
	v_mul_f32_e32 v250, v248, v250
	v_mul_f32_e32 v251, v200, v251
	v_mul_f32_e32 v252, v249, v252
	v_mul_f32_e32 v253, v201, v253
	v_mul_f32_e32 v66, v66, v250
	v_mul_f32_e32 v67, v67, v251
	v_mul_f32_e32 v68, v68, v252
	v_mul_f32_e32 v69, v69, v253
	v_add_co_u32_e32 v248, vcc, 0x360800, v130
	s_nop 1
	v_addc_co_u32_e32 v249, vcc, 0, v131, vcc
	global_load_dwordx2 v[132:133], v[248:249], off offset:-2048
	global_load_dwordx2 v[134:135], v[248:249], off offset:2048
	global_load_dwordx2 v[136:137], v[248:249], off offset:-2016
	global_load_dwordx2 v[138:139], v[248:249], off offset:2080
	global_load_dwordx2 v[140:141], v[248:249], off offset:-1792
	global_load_dwordx2 v[142:143], v[248:249], off offset:2304
	global_load_dwordx2 v[144:145], v[248:249], off offset:-1760
	global_load_dwordx2 v[146:147], v[248:249], off offset:2336
	v_add_co_u32_e32 v250, vcc, 0x3cc800, v130
	s_nop 1
	v_addc_co_u32_e32 v251, vcc, 0, v131, vcc
	global_load_dwordx2 v[148:149], v[250:251], off offset:-2048
	global_load_dwordx2 v[150:151], v[250:251], off offset:2048
	global_load_dwordx2 v[152:153], v[250:251], off offset:-2016
	global_load_dwordx2 v[154:155], v[250:251], off offset:2080
	global_load_dwordx2 v[156:157], v[250:251], off offset:-1792
	global_load_dwordx2 v[158:159], v[250:251], off offset:2304
	global_load_dwordx2 v[160:161], v[250:251], off offset:-1760
	global_load_dwordx2 v[162:163], v[250:251], off offset:2336
	v_add_co_u32_e32 v248, vcc, 0x438800, v130
	s_nop 1
	v_addc_co_u32_e32 v249, vcc, 0, v131, vcc
	global_load_dwordx2 v[164:165], v[248:249], off offset:-2048
	global_load_dwordx2 v[166:167], v[248:249], off offset:2048
	global_load_dwordx2 v[168:169], v[248:249], off offset:-2016
	global_load_dwordx2 v[170:171], v[248:249], off offset:2080
	global_load_dwordx2 v[172:173], v[248:249], off offset:-1792
	global_load_dwordx2 v[174:175], v[248:249], off offset:2304
	global_load_dwordx2 v[176:177], v[248:249], off offset:-1760
	global_load_dwordx2 v[178:179], v[248:249], off offset:2336
	v_add_co_u32_e32 v250, vcc, 0x4a4800, v130
	s_nop 1
	v_addc_co_u32_e32 v251, vcc, 0, v131, vcc
	global_load_dwordx2 v[180:181], v[250:251], off offset:-2048
	global_load_dwordx2 v[182:183], v[250:251], off offset:2048
	global_load_dwordx2 v[184:185], v[250:251], off offset:-2016
	global_load_dwordx2 v[186:187], v[250:251], off offset:2080
	global_load_dwordx2 v[188:189], v[250:251], off offset:-1792
	global_load_dwordx2 v[198:199], v[250:251], off offset:2304
	global_load_dwordx2 v[200:201], v[250:251], off offset:-1760
	global_load_dwordx2 v[202:203], v[250:251], off offset:2336
	s_waitcnt vmcnt(30)
	v_lshlrev_b32_e32 v248, 16, v134
	v_and_b32_e32 v134, 0xffff0000, v134
	v_lshlrev_b32_e32 v249, 16, v135
	v_and_b32_e32 v135, 0xffff0000, v135
	v_max_f32_e32 v248, 0xda24260, v248
	v_max_f32_e32 v134, 0xda24260, v134
	v_max_f32_e32 v249, 0xda24260, v249
	v_max_f32_e32 v135, 0xda24260, v135
	v_rcp_f32_e32 v250, v248
	v_rcp_f32_e32 v251, v134
	v_rcp_f32_e32 v252, v249
	v_rcp_f32_e32 v253, v135
	v_fma_f32 v248, -v248, v250, 1.0
	v_fma_f32 v134, -v134, v251, 1.0
	v_fma_f32 v249, -v249, v252, 1.0
	v_fma_f32 v135, -v135, v253, 1.0
	v_fmac_f32_e32 v250, v248, v250
	v_fmac_f32_e32 v251, v134, v251
	v_fmac_f32_e32 v252, v249, v252
	v_fmac_f32_e32 v253, v135, v253
	v_lshlrev_b32_e32 v248, 16, v132
	v_and_b32_e32 v132, 0xffff0000, v132
	v_lshlrev_b32_e32 v249, 16, v133
	v_and_b32_e32 v133, 0xffff0000, v133
	v_mul_f32_e32 v250, v248, v250
	v_mul_f32_e32 v251, v132, v251
	v_mul_f32_e32 v252, v249, v252
	v_mul_f32_e32 v253, v133, v253
	v_mul_f32_e32 v62, v62, v250
	v_mul_f32_e32 v63, v63, v251
	v_mul_f32_e32 v64, v64, v252
	v_mul_f32_e32 v65, v65, v253
	s_waitcnt vmcnt(28)
	v_lshlrev_b32_e32 v248, 16, v138
	v_and_b32_e32 v138, 0xffff0000, v138
	v_lshlrev_b32_e32 v249, 16, v139
	v_and_b32_e32 v139, 0xffff0000, v139
	v_max_f32_e32 v248, 0xda24260, v248
	v_max_f32_e32 v138, 0xda24260, v138
	v_max_f32_e32 v249, 0xda24260, v249
	v_max_f32_e32 v139, 0xda24260, v139
	v_rcp_f32_e32 v250, v248
	v_rcp_f32_e32 v251, v138
	v_rcp_f32_e32 v252, v249
	v_rcp_f32_e32 v253, v139
	v_fma_f32 v248, -v248, v250, 1.0
	v_fma_f32 v138, -v138, v251, 1.0
	v_fma_f32 v249, -v249, v252, 1.0
	v_fma_f32 v139, -v139, v253, 1.0
	v_fmac_f32_e32 v250, v248, v250
	v_fmac_f32_e32 v251, v138, v251
	v_fmac_f32_e32 v252, v249, v252
	v_fmac_f32_e32 v253, v139, v253
	v_lshlrev_b32_e32 v248, 16, v136
	v_and_b32_e32 v136, 0xffff0000, v136
	v_lshlrev_b32_e32 v249, 16, v137
	v_and_b32_e32 v137, 0xffff0000, v137
	v_mul_f32_e32 v250, v248, v250
	v_mul_f32_e32 v251, v136, v251
	v_mul_f32_e32 v252, v249, v252
	v_mul_f32_e32 v253, v137, v253
	v_mul_f32_e32 v58, v58, v250
	v_mul_f32_e32 v59, v59, v251
	v_mul_f32_e32 v60, v60, v252
	v_mul_f32_e32 v61, v61, v253
	s_waitcnt vmcnt(26)
	v_lshlrev_b32_e32 v248, 16, v142
	v_and_b32_e32 v142, 0xffff0000, v142
	v_lshlrev_b32_e32 v249, 16, v143
	v_and_b32_e32 v143, 0xffff0000, v143
	v_max_f32_e32 v248, 0xda24260, v248
	v_max_f32_e32 v142, 0xda24260, v142
	v_max_f32_e32 v249, 0xda24260, v249
	v_max_f32_e32 v143, 0xda24260, v143
	v_rcp_f32_e32 v250, v248
	v_rcp_f32_e32 v251, v142
	v_rcp_f32_e32 v252, v249
	v_rcp_f32_e32 v253, v143
	v_fma_f32 v248, -v248, v250, 1.0
	v_fma_f32 v142, -v142, v251, 1.0
	v_fma_f32 v249, -v249, v252, 1.0
	v_fma_f32 v143, -v143, v253, 1.0
	v_fmac_f32_e32 v250, v248, v250
	v_fmac_f32_e32 v251, v142, v251
	v_fmac_f32_e32 v252, v249, v252
	v_fmac_f32_e32 v253, v143, v253
	v_lshlrev_b32_e32 v248, 16, v140
	v_and_b32_e32 v140, 0xffff0000, v140
	v_lshlrev_b32_e32 v249, 16, v141
	v_and_b32_e32 v141, 0xffff0000, v141
	v_mul_f32_e32 v250, v248, v250
	v_mul_f32_e32 v251, v140, v251
	v_mul_f32_e32 v252, v249, v252
	v_mul_f32_e32 v253, v141, v253
	v_mul_f32_e32 v30, v30, v250
	v_mul_f32_e32 v31, v31, v251
	v_mul_f32_e32 v32, v32, v252
	v_mul_f32_e32 v33, v33, v253
	s_waitcnt vmcnt(24)
	v_lshlrev_b32_e32 v248, 16, v146
	v_and_b32_e32 v146, 0xffff0000, v146
	v_lshlrev_b32_e32 v249, 16, v147
	v_and_b32_e32 v147, 0xffff0000, v147
	v_max_f32_e32 v248, 0xda24260, v248
	v_max_f32_e32 v146, 0xda24260, v146
	v_max_f32_e32 v249, 0xda24260, v249
	v_max_f32_e32 v147, 0xda24260, v147
	v_rcp_f32_e32 v250, v248
	v_rcp_f32_e32 v251, v146
	v_rcp_f32_e32 v252, v249
	v_rcp_f32_e32 v253, v147
	v_fma_f32 v248, -v248, v250, 1.0
	v_fma_f32 v146, -v146, v251, 1.0
	v_fma_f32 v249, -v249, v252, 1.0
	v_fma_f32 v147, -v147, v253, 1.0
	v_fmac_f32_e32 v250, v248, v250
	v_fmac_f32_e32 v251, v146, v251
	v_fmac_f32_e32 v252, v249, v252
	v_fmac_f32_e32 v253, v147, v253
	v_lshlrev_b32_e32 v248, 16, v144
	v_and_b32_e32 v144, 0xffff0000, v144
	v_lshlrev_b32_e32 v249, 16, v145
	v_and_b32_e32 v145, 0xffff0000, v145
	v_mul_f32_e32 v250, v248, v250
	v_mul_f32_e32 v251, v144, v251
	v_mul_f32_e32 v252, v249, v252
	v_mul_f32_e32 v253, v145, v253
	v_mul_f32_e32 v26, v26, v250
	v_mul_f32_e32 v27, v27, v251
	v_mul_f32_e32 v28, v28, v252
	v_mul_f32_e32 v29, v29, v253
	s_waitcnt vmcnt(22)
	v_lshlrev_b32_e32 v248, 16, v150
	v_and_b32_e32 v150, 0xffff0000, v150
	v_lshlrev_b32_e32 v249, 16, v151
	v_and_b32_e32 v151, 0xffff0000, v151
	v_max_f32_e32 v248, 0xda24260, v248
	v_max_f32_e32 v150, 0xda24260, v150
	v_max_f32_e32 v249, 0xda24260, v249
	v_max_f32_e32 v151, 0xda24260, v151
	v_rcp_f32_e32 v250, v248
	v_rcp_f32_e32 v251, v150
	v_rcp_f32_e32 v252, v249
	v_rcp_f32_e32 v253, v151
	v_fma_f32 v248, -v248, v250, 1.0
	v_fma_f32 v150, -v150, v251, 1.0
	v_fma_f32 v249, -v249, v252, 1.0
	v_fma_f32 v151, -v151, v253, 1.0
	v_fmac_f32_e32 v250, v248, v250
	v_fmac_f32_e32 v251, v150, v251
	v_fmac_f32_e32 v252, v249, v252
	v_fmac_f32_e32 v253, v151, v253
	v_lshlrev_b32_e32 v248, 16, v148
	v_and_b32_e32 v148, 0xffff0000, v148
	v_lshlrev_b32_e32 v249, 16, v149
	v_and_b32_e32 v149, 0xffff0000, v149
	v_mul_f32_e32 v250, v248, v250
	v_mul_f32_e32 v251, v148, v251
	v_mul_f32_e32 v252, v249, v252
	v_mul_f32_e32 v253, v149, v253
	v_mul_f32_e32 v54, v54, v250
	v_mul_f32_e32 v55, v55, v251
	v_mul_f32_e32 v56, v56, v252
	v_mul_f32_e32 v57, v57, v253
	s_waitcnt vmcnt(20)
	v_lshlrev_b32_e32 v248, 16, v154
	v_and_b32_e32 v154, 0xffff0000, v154
	v_lshlrev_b32_e32 v249, 16, v155
	v_and_b32_e32 v155, 0xffff0000, v155
	v_max_f32_e32 v248, 0xda24260, v248
	v_max_f32_e32 v154, 0xda24260, v154
	v_max_f32_e32 v249, 0xda24260, v249
	v_max_f32_e32 v155, 0xda24260, v155
	v_rcp_f32_e32 v250, v248
	v_rcp_f32_e32 v251, v154
	v_rcp_f32_e32 v252, v249
	v_rcp_f32_e32 v253, v155
	v_fma_f32 v248, -v248, v250, 1.0
	v_fma_f32 v154, -v154, v251, 1.0
	v_fma_f32 v249, -v249, v252, 1.0
	v_fma_f32 v155, -v155, v253, 1.0
	v_fmac_f32_e32 v250, v248, v250
	v_fmac_f32_e32 v251, v154, v251
	v_fmac_f32_e32 v252, v249, v252
	v_fmac_f32_e32 v253, v155, v253
	v_lshlrev_b32_e32 v248, 16, v152
	v_and_b32_e32 v152, 0xffff0000, v152
	v_lshlrev_b32_e32 v249, 16, v153
	v_and_b32_e32 v153, 0xffff0000, v153
	v_mul_f32_e32 v250, v248, v250
	v_mul_f32_e32 v251, v152, v251
	v_mul_f32_e32 v252, v249, v252
	v_mul_f32_e32 v253, v153, v253
	v_mul_f32_e32 v50, v50, v250
	v_mul_f32_e32 v51, v51, v251
	v_mul_f32_e32 v52, v52, v252
	v_mul_f32_e32 v53, v53, v253
	s_waitcnt vmcnt(18)
	v_lshlrev_b32_e32 v248, 16, v158
	v_and_b32_e32 v158, 0xffff0000, v158
	v_lshlrev_b32_e32 v249, 16, v159
	v_and_b32_e32 v159, 0xffff0000, v159
	v_max_f32_e32 v248, 0xda24260, v248
	v_max_f32_e32 v158, 0xda24260, v158
	v_max_f32_e32 v249, 0xda24260, v249
	v_max_f32_e32 v159, 0xda24260, v159
	v_rcp_f32_e32 v250, v248
	v_rcp_f32_e32 v251, v158
	v_rcp_f32_e32 v252, v249
	v_rcp_f32_e32 v253, v159
	v_fma_f32 v248, -v248, v250, 1.0
	v_fma_f32 v158, -v158, v251, 1.0
	v_fma_f32 v249, -v249, v252, 1.0
	v_fma_f32 v159, -v159, v253, 1.0
	v_fmac_f32_e32 v250, v248, v250
	v_fmac_f32_e32 v251, v158, v251
	v_fmac_f32_e32 v252, v249, v252
	v_fmac_f32_e32 v253, v159, v253
	v_lshlrev_b32_e32 v248, 16, v156
	v_and_b32_e32 v156, 0xffff0000, v156
	v_lshlrev_b32_e32 v249, 16, v157
	v_and_b32_e32 v157, 0xffff0000, v157
	v_mul_f32_e32 v250, v248, v250
	v_mul_f32_e32 v251, v156, v251
	v_mul_f32_e32 v252, v249, v252
	v_mul_f32_e32 v253, v157, v253
	v_mul_f32_e32 v22, v22, v250
	v_mul_f32_e32 v23, v23, v251
	v_mul_f32_e32 v24, v24, v252
	v_mul_f32_e32 v25, v25, v253
	s_waitcnt vmcnt(16)
	v_lshlrev_b32_e32 v248, 16, v162
	v_and_b32_e32 v162, 0xffff0000, v162
	v_lshlrev_b32_e32 v249, 16, v163
	v_and_b32_e32 v163, 0xffff0000, v163
	v_max_f32_e32 v248, 0xda24260, v248
	v_max_f32_e32 v162, 0xda24260, v162
	v_max_f32_e32 v249, 0xda24260, v249
	v_max_f32_e32 v163, 0xda24260, v163
	v_rcp_f32_e32 v250, v248
	v_rcp_f32_e32 v251, v162
	v_rcp_f32_e32 v252, v249
	v_rcp_f32_e32 v253, v163
	v_fma_f32 v248, -v248, v250, 1.0
	v_fma_f32 v162, -v162, v251, 1.0
	v_fma_f32 v249, -v249, v252, 1.0
	v_fma_f32 v163, -v163, v253, 1.0
	v_fmac_f32_e32 v250, v248, v250
	v_fmac_f32_e32 v251, v162, v251
	v_fmac_f32_e32 v252, v249, v252
	v_fmac_f32_e32 v253, v163, v253
	v_lshlrev_b32_e32 v248, 16, v160
	v_and_b32_e32 v160, 0xffff0000, v160
	v_lshlrev_b32_e32 v249, 16, v161
	v_and_b32_e32 v161, 0xffff0000, v161
	v_mul_f32_e32 v250, v248, v250
	v_mul_f32_e32 v251, v160, v251
	v_mul_f32_e32 v252, v249, v252
	v_mul_f32_e32 v253, v161, v253
	v_mul_f32_e32 v18, v18, v250
	v_mul_f32_e32 v19, v19, v251
	v_mul_f32_e32 v20, v20, v252
	v_mul_f32_e32 v21, v21, v253
	s_waitcnt vmcnt(14)
	v_lshlrev_b32_e32 v248, 16, v166
	v_and_b32_e32 v166, 0xffff0000, v166
	v_lshlrev_b32_e32 v249, 16, v167
	v_and_b32_e32 v167, 0xffff0000, v167
	v_max_f32_e32 v248, 0xda24260, v248
	v_max_f32_e32 v166, 0xda24260, v166
	v_max_f32_e32 v249, 0xda24260, v249
	v_max_f32_e32 v167, 0xda24260, v167
	v_rcp_f32_e32 v250, v248
	v_rcp_f32_e32 v251, v166
	v_rcp_f32_e32 v252, v249
	v_rcp_f32_e32 v253, v167
	v_fma_f32 v248, -v248, v250, 1.0
	v_fma_f32 v166, -v166, v251, 1.0
	v_fma_f32 v249, -v249, v252, 1.0
	v_fma_f32 v167, -v167, v253, 1.0
	v_fmac_f32_e32 v250, v248, v250
	v_fmac_f32_e32 v251, v166, v251
	v_fmac_f32_e32 v252, v249, v252
	v_fmac_f32_e32 v253, v167, v253
	v_lshlrev_b32_e32 v248, 16, v164
	v_and_b32_e32 v164, 0xffff0000, v164
	v_lshlrev_b32_e32 v249, 16, v165
	v_and_b32_e32 v165, 0xffff0000, v165
	v_mul_f32_e32 v250, v248, v250
	v_mul_f32_e32 v251, v164, v251
	v_mul_f32_e32 v252, v249, v252
	v_mul_f32_e32 v253, v165, v253
	v_mul_f32_e32 v46, v46, v250
	v_mul_f32_e32 v47, v47, v251
	v_mul_f32_e32 v48, v48, v252
	v_mul_f32_e32 v49, v49, v253
	s_waitcnt vmcnt(12)
	v_lshlrev_b32_e32 v248, 16, v170
	v_and_b32_e32 v170, 0xffff0000, v170
	v_lshlrev_b32_e32 v249, 16, v171
	v_and_b32_e32 v171, 0xffff0000, v171
	v_max_f32_e32 v248, 0xda24260, v248
	v_max_f32_e32 v170, 0xda24260, v170
	v_max_f32_e32 v249, 0xda24260, v249
	v_max_f32_e32 v171, 0xda24260, v171
	v_rcp_f32_e32 v250, v248
	v_rcp_f32_e32 v251, v170
	v_rcp_f32_e32 v252, v249
	v_rcp_f32_e32 v253, v171
	v_fma_f32 v248, -v248, v250, 1.0
	v_fma_f32 v170, -v170, v251, 1.0
	v_fma_f32 v249, -v249, v252, 1.0
	v_fma_f32 v171, -v171, v253, 1.0
	v_fmac_f32_e32 v250, v248, v250
	v_fmac_f32_e32 v251, v170, v251
	v_fmac_f32_e32 v252, v249, v252
	v_fmac_f32_e32 v253, v171, v253
	v_lshlrev_b32_e32 v248, 16, v168
	v_and_b32_e32 v168, 0xffff0000, v168
	v_lshlrev_b32_e32 v249, 16, v169
	v_and_b32_e32 v169, 0xffff0000, v169
	v_mul_f32_e32 v250, v248, v250
	v_mul_f32_e32 v251, v168, v251
	v_mul_f32_e32 v252, v249, v252
	v_mul_f32_e32 v253, v169, v253
	v_mul_f32_e32 v42, v42, v250
	v_mul_f32_e32 v43, v43, v251
	v_mul_f32_e32 v44, v44, v252
	v_mul_f32_e32 v45, v45, v253
	s_waitcnt vmcnt(10)
	v_lshlrev_b32_e32 v248, 16, v174
	v_and_b32_e32 v174, 0xffff0000, v174
	v_lshlrev_b32_e32 v249, 16, v175
	v_and_b32_e32 v175, 0xffff0000, v175
	v_max_f32_e32 v248, 0xda24260, v248
	v_max_f32_e32 v174, 0xda24260, v174
	v_max_f32_e32 v249, 0xda24260, v249
	v_max_f32_e32 v175, 0xda24260, v175
	v_rcp_f32_e32 v250, v248
	v_rcp_f32_e32 v251, v174
	v_rcp_f32_e32 v252, v249
	v_rcp_f32_e32 v253, v175
	v_fma_f32 v248, -v248, v250, 1.0
	v_fma_f32 v174, -v174, v251, 1.0
	v_fma_f32 v249, -v249, v252, 1.0
	v_fma_f32 v175, -v175, v253, 1.0
	v_fmac_f32_e32 v250, v248, v250
	v_fmac_f32_e32 v251, v174, v251
	v_fmac_f32_e32 v252, v249, v252
	v_fmac_f32_e32 v253, v175, v253
	v_lshlrev_b32_e32 v248, 16, v172
	v_and_b32_e32 v172, 0xffff0000, v172
	v_lshlrev_b32_e32 v249, 16, v173
	v_and_b32_e32 v173, 0xffff0000, v173
	v_mul_f32_e32 v250, v248, v250
	v_mul_f32_e32 v251, v172, v251
	v_mul_f32_e32 v252, v249, v252
	v_mul_f32_e32 v253, v173, v253
	v_mul_f32_e32 v14, v14, v250
	v_mul_f32_e32 v15, v15, v251
	v_mul_f32_e32 v16, v16, v252
	v_mul_f32_e32 v17, v17, v253
	s_waitcnt vmcnt(8)
	v_lshlrev_b32_e32 v248, 16, v178
	v_and_b32_e32 v178, 0xffff0000, v178
	v_lshlrev_b32_e32 v249, 16, v179
	v_and_b32_e32 v179, 0xffff0000, v179
	v_max_f32_e32 v248, 0xda24260, v248
	v_max_f32_e32 v178, 0xda24260, v178
	v_max_f32_e32 v249, 0xda24260, v249
	v_max_f32_e32 v179, 0xda24260, v179
	v_rcp_f32_e32 v250, v248
	v_rcp_f32_e32 v251, v178
	v_rcp_f32_e32 v252, v249
	v_rcp_f32_e32 v253, v179
	v_fma_f32 v248, -v248, v250, 1.0
	v_fma_f32 v178, -v178, v251, 1.0
	v_fma_f32 v249, -v249, v252, 1.0
	v_fma_f32 v179, -v179, v253, 1.0
	v_fmac_f32_e32 v250, v248, v250
	v_fmac_f32_e32 v251, v178, v251
	v_fmac_f32_e32 v252, v249, v252
	v_fmac_f32_e32 v253, v179, v253
	v_lshlrev_b32_e32 v248, 16, v176
	v_and_b32_e32 v176, 0xffff0000, v176
	v_lshlrev_b32_e32 v249, 16, v177
	v_and_b32_e32 v177, 0xffff0000, v177
	v_mul_f32_e32 v250, v248, v250
	v_mul_f32_e32 v251, v176, v251
	v_mul_f32_e32 v252, v249, v252
	v_mul_f32_e32 v253, v177, v253
	v_mul_f32_e32 v10, v10, v250
	v_mul_f32_e32 v11, v11, v251
	v_mul_f32_e32 v12, v12, v252
	v_mul_f32_e32 v13, v13, v253
	s_waitcnt vmcnt(6)
	v_lshlrev_b32_e32 v248, 16, v182
	v_and_b32_e32 v182, 0xffff0000, v182
	v_lshlrev_b32_e32 v249, 16, v183
	v_and_b32_e32 v183, 0xffff0000, v183
	v_max_f32_e32 v248, 0xda24260, v248
	v_max_f32_e32 v182, 0xda24260, v182
	v_max_f32_e32 v249, 0xda24260, v249
	v_max_f32_e32 v183, 0xda24260, v183
	v_rcp_f32_e32 v250, v248
	v_rcp_f32_e32 v251, v182
	v_rcp_f32_e32 v252, v249
	v_rcp_f32_e32 v253, v183
	v_fma_f32 v248, -v248, v250, 1.0
	v_fma_f32 v182, -v182, v251, 1.0
	v_fma_f32 v249, -v249, v252, 1.0
	v_fma_f32 v183, -v183, v253, 1.0
	v_fmac_f32_e32 v250, v248, v250
	v_fmac_f32_e32 v251, v182, v251
	v_fmac_f32_e32 v252, v249, v252
	v_fmac_f32_e32 v253, v183, v253
	v_lshlrev_b32_e32 v248, 16, v180
	v_and_b32_e32 v180, 0xffff0000, v180
	v_lshlrev_b32_e32 v249, 16, v181
	v_and_b32_e32 v181, 0xffff0000, v181
	v_mul_f32_e32 v250, v248, v250
	v_mul_f32_e32 v251, v180, v251
	v_mul_f32_e32 v252, v249, v252
	v_mul_f32_e32 v253, v181, v253
	v_mul_f32_e32 v38, v38, v250
	v_mul_f32_e32 v39, v39, v251
	v_mul_f32_e32 v40, v40, v252
	v_mul_f32_e32 v41, v41, v253
	s_waitcnt vmcnt(4)
	v_lshlrev_b32_e32 v248, 16, v186
	v_and_b32_e32 v186, 0xffff0000, v186
	v_lshlrev_b32_e32 v249, 16, v187
	v_and_b32_e32 v187, 0xffff0000, v187
	v_max_f32_e32 v248, 0xda24260, v248
	v_max_f32_e32 v186, 0xda24260, v186
	v_max_f32_e32 v249, 0xda24260, v249
	v_max_f32_e32 v187, 0xda24260, v187
	v_rcp_f32_e32 v250, v248
	v_rcp_f32_e32 v251, v186
	v_rcp_f32_e32 v252, v249
	v_rcp_f32_e32 v253, v187
	v_fma_f32 v248, -v248, v250, 1.0
	v_fma_f32 v186, -v186, v251, 1.0
	v_fma_f32 v249, -v249, v252, 1.0
	v_fma_f32 v187, -v187, v253, 1.0
	v_fmac_f32_e32 v250, v248, v250
	v_fmac_f32_e32 v251, v186, v251
	v_fmac_f32_e32 v252, v249, v252
	v_fmac_f32_e32 v253, v187, v253
	v_lshlrev_b32_e32 v248, 16, v184
	v_and_b32_e32 v184, 0xffff0000, v184
	v_lshlrev_b32_e32 v249, 16, v185
	v_and_b32_e32 v185, 0xffff0000, v185
	v_mul_f32_e32 v250, v248, v250
	v_mul_f32_e32 v251, v184, v251
	v_mul_f32_e32 v252, v249, v252
	v_mul_f32_e32 v253, v185, v253
	v_mul_f32_e32 v34, v34, v250
	v_mul_f32_e32 v35, v35, v251
	v_mul_f32_e32 v36, v36, v252
	v_mul_f32_e32 v37, v37, v253
	s_waitcnt vmcnt(2)
	v_lshlrev_b32_e32 v248, 16, v198
	v_and_b32_e32 v198, 0xffff0000, v198
	v_lshlrev_b32_e32 v249, 16, v199
	v_and_b32_e32 v199, 0xffff0000, v199
	v_max_f32_e32 v248, 0xda24260, v248
	v_max_f32_e32 v198, 0xda24260, v198
	v_max_f32_e32 v249, 0xda24260, v249
	v_max_f32_e32 v199, 0xda24260, v199
	v_rcp_f32_e32 v250, v248
	v_rcp_f32_e32 v251, v198
	v_rcp_f32_e32 v252, v249
	v_rcp_f32_e32 v253, v199
	v_fma_f32 v248, -v248, v250, 1.0
	v_fma_f32 v198, -v198, v251, 1.0
	v_fma_f32 v249, -v249, v252, 1.0
	v_fma_f32 v199, -v199, v253, 1.0
	v_fmac_f32_e32 v250, v248, v250
	v_fmac_f32_e32 v251, v198, v251
	v_fmac_f32_e32 v252, v249, v252
	v_fmac_f32_e32 v253, v199, v253
	v_lshlrev_b32_e32 v248, 16, v188
	v_and_b32_e32 v188, 0xffff0000, v188
	v_lshlrev_b32_e32 v249, 16, v189
	v_and_b32_e32 v189, 0xffff0000, v189
	v_mul_f32_e32 v250, v248, v250
	v_mul_f32_e32 v251, v188, v251
	v_mul_f32_e32 v252, v249, v252
	v_mul_f32_e32 v253, v189, v253
	v_mul_f32_e32 v6, v6, v250
	v_mul_f32_e32 v7, v7, v251
	v_mul_f32_e32 v8, v8, v252
	v_mul_f32_e32 v9, v9, v253
	s_waitcnt vmcnt(0)
	v_lshlrev_b32_e32 v248, 16, v202
	v_and_b32_e32 v202, 0xffff0000, v202
	v_lshlrev_b32_e32 v249, 16, v203
	v_and_b32_e32 v203, 0xffff0000, v203
	v_max_f32_e32 v248, 0xda24260, v248
	v_max_f32_e32 v202, 0xda24260, v202
	v_max_f32_e32 v249, 0xda24260, v249
	v_max_f32_e32 v203, 0xda24260, v203
	v_rcp_f32_e32 v250, v248
	v_rcp_f32_e32 v251, v202
	v_rcp_f32_e32 v252, v249
	v_rcp_f32_e32 v253, v203
	v_fma_f32 v248, -v248, v250, 1.0
	v_fma_f32 v202, -v202, v251, 1.0
	v_fma_f32 v249, -v249, v252, 1.0
	v_fma_f32 v203, -v203, v253, 1.0
	v_fmac_f32_e32 v250, v248, v250
	v_fmac_f32_e32 v251, v202, v251
	v_fmac_f32_e32 v252, v249, v252
	v_fmac_f32_e32 v253, v203, v253
	v_lshlrev_b32_e32 v248, 16, v200
	v_and_b32_e32 v200, 0xffff0000, v200
	v_lshlrev_b32_e32 v249, 16, v201
	v_and_b32_e32 v201, 0xffff0000, v201
	v_mul_f32_e32 v250, v248, v250
	v_mul_f32_e32 v251, v200, v251
	v_mul_f32_e32 v252, v249, v252
	v_mul_f32_e32 v253, v201, v253
	v_mul_f32_e32 v2, v2, v250
	v_mul_f32_e32 v3, v3, v251
	v_mul_f32_e32 v4, v4, v252
	v_mul_f32_e32 v5, v5, v253
	s_branch .LBB0_254

.LBB0_284:
	s_and_b64 vcc, exec, s[6:7]
	s_cbranch_vccz .LBB0_247
	s_ashr_i32 s2, s94, 8
	s_cmp_lt_i32 s2, 16
	s_cselect_b64 s[6:7], -1, 0
	s_and_b64 vcc, exec, s[6:7]
	s_cbranch_vccnz .LBB0_768
	s_sub_i32 s6, s2, 18
	s_cmp_gt_u32 s6, 3
	s_cselect_b64 s[6:7], -1, 0
	s_cmp_lt_u32 s2, 30
	s_cselect_b64 s[8:9], -1, 0
	s_and_b64 s[8:9], s[8:9], s[6:7]
	s_mov_b64 s[6:7], -1
	s_and_b64 vcc, exec, s[8:9]
	s_cbranch_vccz .LBB0_768
	v_subrev_u32_e32 v130, s60, v198
	v_subrev_u32_e32 v131, s94, v200
	s_cmp_lt_i32 s2, 18
	s_cselect_b32 s13, 8, 10
	s_cselect_b32 s33, 1, 0
	s_sub_i32 s83, s2, 22
	s_and_b32 s83, s83, 3
	s_lshl_b32 s83, s83, 8
	s_cmp_lt_i32 s2, 18
	s_cselect_b32 s83, 0, s83
	s_cmp_eq_u32 s2, 17
	s_cselect_b32 s97, 1, 0
	s_cmp_gt_i32 s2, 25
	s_cselect_b32 s97, 1, s97
	s_add_i32 s84, s13, 1
	s_add_i32 s85, s13, 2
	s_cmpk_lt_i32 s60, 0x1000
	s_cbranch_scc0 .Lkv_lat
	s_lshr_b32 s24, s60, 8
	s_lshl_b32 s25, s24, 1
	s_add_i32 s25, s25, s96
	s_lshl_b32 s25, s25, 8
	s_lshl_b32 s25, s25, s13
	s_add_i32 s25, s25, s83
	s_lshl_b32 s25, s25, 2
	s_cmp_eq_u32 s33, 1
	s_mov_b32 s28, 0x5000000
	s_cselect_b32 s28, 0x4000000, s28
	s_mov_b32 s29, 0x7000000
	s_cselect_b32 s29, 0x4800000, s29
	s_cmp_eq_u32 s97, 1
	s_cselect_b32 s28, s29, s28
	s_add_u32 s25, s25, s28
	s_add_u32 s8, s20, s25
	s_addc_u32 s9, s21, 0
	v_lshlrev_b32_e32 v133, s85, v130
	v_lshl_add_u32 v133, v131, 2, v133
	s_lshl_b32 s70, 16, s85
	s_mul_i32 s71, s70, 5
	s_cmp_eq_u32 s97, 1
	s_cbranch_scc1 .Lkv_ctx_v
	s_add_i32 s28, s13, 9
	s_lshl_b32 s25, s24, s28
	s_lshl_b32 s28, s83, 1
	s_add_u32 s25, s25, s28
	s_cmp_eq_u32 s33, 1
	s_mov_b32 s28, 0x2de50000
	s_cselect_b32 s28, 0x2dc50000, s28
	s_add_u32 s25, s25, s28
	s_add_u32 s6, s22, s25
	s_addc_u32 s7, s23, 0
	s_branch .Lkv_k_body_ctx
.Lkv_ctx_v:
	s_lshl_b32 s25, s24, s13
	s_add_i32 s25, s25, s83
	s_lshl_b32 s25, s25, 9
	s_cmp_eq_u32 s33, 1
	s_mov_b32 s28, 0x2e850000
	s_cselect_b32 s28, 0x2e650000, s28
	s_add_u32 s25, s25, s28
	s_add_u32 s6, s22, s25
	s_addc_u32 s7, s23, 0
	s_movk_i32 s76, 0x200
	s_branch .Lkv_v_body_ctx
.Lkv_lat:
	s_sub_i32 s24, s60, 0x1000
	s_and_b32 s25, s24, 0x7ff
	s_lshr_b32 s24, s24, 11
	s_cmp_eq_u32 s97, 1
	s_cbranch_scc1 .Lkv_lat_v
	s_mul_i32 s28, s24, 0xa00
	s_add_i32 s28, s28, s25
	s_addk_i32 s28, 0x200
	s_lshl_b32 s28, s28, s84
	s_lshl_b32 s29, s83, 1
	s_add_u32 s28, s28, s29
	s_cmp_eq_u32 s33, 1
	s_mov_b32 s29, 0x2f550000
	s_cselect_b32 s29, 0x2f050000, s29
	s_mov_b32 s30, 0xa00000
	s_cselect_b32 s30, 0x280000, s30
	s_mul_i32 s30, s30, s96
	s_add_u32 s28, s28, s29
	s_add_u32 s28, s28, s30
	s_add_u32 s6, s22, s28
	s_addc_u32 s7, s23, 0
	s_branch .Lkv_k_body_lat
.Lkv_lat_v:
	s_lshl_b32 s28, s24, s13
	s_add_i32 s28, s28, s83
	s_mul_i32 s28, s28, 0xa00
	s_add_i32 s28, s28, s25
	s_addk_i32 s28, 0x200
	s_lshl_b32 s28, s28, 1
	s_cmp_eq_u32 s33, 1
	s_mov_b32 s29, 0x30e50000
	s_cselect_b32 s29, 0x30950000, s29
	s_mov_b32 s30, 0xa00000
	s_cselect_b32 s30, 0x280000, s30
	s_mul_i32 s30, s30, s96
	s_add_u32 s28, s28, s29
	s_add_u32 s28, s28, s30
	s_add_u32 s6, s22, s28
	s_addc_u32 s7, s23, 0
	s_movk_i32 s76, 0x1400
	s_branch .Lkv_v_body_lat
.Lkv_k_body_ctx:
	v_lshlrev_b32_e32 v132, s84, v130
	v_lshl_add_u32 v132, v131, 1, v132
	s_lshl_b32 s58, 16, s84
	s_mul_i32 s59, s58, 5
	v_cvt_pk_bf16_f32 v134, v126, v127
	v_cvt_pk_bf16_f32 v135, v128, v129
	global_store_dwordx2 v132, v[134:135], s[6:7] offset:0
	global_store_dwordx4 v133, v[126:129], s[8:9] offset:0
	v_cvt_pk_bf16_f32 v136, v122, v123
	v_cvt_pk_bf16_f32 v137, v124, v125
	global_store_dwordx2 v132, v[136:137], s[6:7] offset:32
	global_store_dwordx4 v133, v[122:125], s[8:9] offset:64
	v_cvt_pk_bf16_f32 v138, v94, v95
	v_cvt_pk_bf16_f32 v139, v96, v97
	global_store_dwordx2 v132, v[138:139], s[6:7] offset:256
	global_store_dwordx4 v133, v[94:97], s[8:9] offset:512
	v_cvt_pk_bf16_f32 v140, v90, v91
	v_cvt_pk_bf16_f32 v141, v92, v93
	global_store_dwordx2 v132, v[140:141], s[6:7] offset:288
	global_store_dwordx4 v133, v[90:93], s[8:9] offset:576
	s_add_u32 s6, s6, s58
	s_addc_u32 s7, s7, 0
	s_add_u32 s8, s8, s70
	s_addc_u32 s9, s9, 0
	v_cvt_pk_bf16_f32 v142, v118, v119
	v_cvt_pk_bf16_f32 v143, v120, v121
	global_store_dwordx2 v132, v[142:143], s[6:7] offset:0
	global_store_dwordx4 v133, v[118:121], s[8:9] offset:0
	v_cvt_pk_bf16_f32 v144, v114, v115
	v_cvt_pk_bf16_f32 v145, v116, v117
	global_store_dwordx2 v132, v[144:145], s[6:7] offset:32
	global_store_dwordx4 v133, v[114:117], s[8:9] offset:64
	v_cvt_pk_bf16_f32 v146, v86, v87
	v_cvt_pk_bf16_f32 v147, v88, v89
	global_store_dwordx2 v132, v[146:147], s[6:7] offset:256
	global_store_dwordx4 v133, v[86:89], s[8:9] offset:512
	v_cvt_pk_bf16_f32 v148, v82, v83
	v_cvt_pk_bf16_f32 v149, v84, v85
	global_store_dwordx2 v132, v[148:149], s[6:7] offset:288
	global_store_dwordx4 v133, v[82:85], s[8:9] offset:576
	s_add_u32 s6, s6, s58
	s_addc_u32 s7, s7, 0
	s_add_u32 s8, s8, s70
	s_addc_u32 s9, s9, 0
	v_cvt_pk_bf16_f32 v150, v110, v111
	v_cvt_pk_bf16_f32 v151, v112, v113
	global_store_dwordx2 v132, v[150:151], s[6:7] offset:0
	global_store_dwordx4 v133, v[110:113], s[8:9] offset:0
	v_cvt_pk_bf16_f32 v152, v106, v107
	v_cvt_pk_bf16_f32 v153, v108, v109
	global_store_dwordx2 v132, v[152:153], s[6:7] offset:32
	global_store_dwordx4 v133, v[106:109], s[8:9] offset:64
	v_cvt_pk_bf16_f32 v154, v78, v79
	v_cvt_pk_bf16_f32 v155, v80, v81
	global_store_dwordx2 v132, v[154:155], s[6:7] offset:256
	global_store_dwordx4 v133, v[78:81], s[8:9] offset:512
	v_cvt_pk_bf16_f32 v156, v74, v75
	v_cvt_pk_bf16_f32 v157, v76, v77
	global_store_dwordx2 v132, v[156:157], s[6:7] offset:288
	global_store_dwordx4 v133, v[74:77], s[8:9] offset:576
	s_add_u32 s6, s6, s58
	s_addc_u32 s7, s7, 0
	s_add_u32 s8, s8, s70
	s_addc_u32 s9, s9, 0
	v_cvt_pk_bf16_f32 v158, v102, v103
	v_cvt_pk_bf16_f32 v159, v104, v105
	global_store_dwordx2 v132, v[158:159], s[6:7] offset:0
	global_store_dwordx4 v133, v[102:105], s[8:9] offset:0
	v_cvt_pk_bf16_f32 v160, v98, v99
	v_cvt_pk_bf16_f32 v161, v100, v101
	global_store_dwordx2 v132, v[160:161], s[6:7] offset:32
	global_store_dwordx4 v133, v[98:101], s[8:9] offset:64
	v_cvt_pk_bf16_f32 v162, v70, v71
	v_cvt_pk_bf16_f32 v163, v72, v73
	global_store_dwordx2 v132, v[162:163], s[6:7] offset:256
	global_store_dwordx4 v133, v[70:73], s[8:9] offset:512
	v_cvt_pk_bf16_f32 v164, v66, v67
	v_cvt_pk_bf16_f32 v165, v68, v69
	global_store_dwordx2 v132, v[164:165], s[6:7] offset:288
	global_store_dwordx4 v133, v[66:69], s[8:9] offset:576
	s_add_u32 s6, s6, s59
	s_addc_u32 s7, s7, 0
	s_add_u32 s8, s8, s71
	s_addc_u32 s9, s9, 0
	v_cvt_pk_bf16_f32 v134, v62, v63
	v_cvt_pk_bf16_f32 v135, v64, v65
	global_store_dwordx2 v132, v[134:135], s[6:7] offset:0
	global_store_dwordx4 v133, v[62:65], s[8:9] offset:0
	v_cvt_pk_bf16_f32 v136, v58, v59
	v_cvt_pk_bf16_f32 v137, v60, v61
	global_store_dwordx2 v132, v[136:137], s[6:7] offset:32
	global_store_dwordx4 v133, v[58:61], s[8:9] offset:64
	v_cvt_pk_bf16_f32 v138, v30, v31
	v_cvt_pk_bf16_f32 v139, v32, v33
	global_store_dwordx2 v132, v[138:139], s[6:7] offset:256
	global_store_dwordx4 v133, v[30:33], s[8:9] offset:512
	v_cvt_pk_bf16_f32 v140, v26, v27
	v_cvt_pk_bf16_f32 v141, v28, v29
	global_store_dwordx2 v132, v[140:141], s[6:7] offset:288
	global_store_dwordx4 v133, v[26:29], s[8:9] offset:576
	s_add_u32 s6, s6, s58
	s_addc_u32 s7, s7, 0
	s_add_u32 s8, s8, s70
	s_addc_u32 s9, s9, 0
	v_cvt_pk_bf16_f32 v142, v54, v55
	v_cvt_pk_bf16_f32 v143, v56, v57
	global_store_dwordx2 v132, v[142:143], s[6:7] offset:0
	global_store_dwordx4 v133, v[54:57], s[8:9] offset:0
	v_cvt_pk_bf16_f32 v144, v50, v51
	v_cvt_pk_bf16_f32 v145, v52, v53
	global_store_dwordx2 v132, v[144:145], s[6:7] offset:32
	global_store_dwordx4 v133, v[50:53], s[8:9] offset:64
	v_cvt_pk_bf16_f32 v146, v22, v23
	v_cvt_pk_bf16_f32 v147, v24, v25
	global_store_dwordx2 v132, v[146:147], s[6:7] offset:256
	global_store_dwordx4 v133, v[22:25], s[8:9] offset:512
	v_cvt_pk_bf16_f32 v148, v18, v19
	v_cvt_pk_bf16_f32 v149, v20, v21
	global_store_dwordx2 v132, v[148:149], s[6:7] offset:288
	global_store_dwordx4 v133, v[18:21], s[8:9] offset:576
	s_add_u32 s6, s6, s58
	s_addc_u32 s7, s7, 0
	s_add_u32 s8, s8, s70
	s_addc_u32 s9, s9, 0
	v_cvt_pk_bf16_f32 v150, v46, v47
	v_cvt_pk_bf16_f32 v151, v48, v49
	global_store_dwordx2 v132, v[150:151], s[6:7] offset:0
	global_store_dwordx4 v133, v[46:49], s[8:9] offset:0
	v_cvt_pk_bf16_f32 v152, v42, v43
	v_cvt_pk_bf16_f32 v153, v44, v45
	global_store_dwordx2 v132, v[152:153], s[6:7] offset:32
	global_store_dwordx4 v133, v[42:45], s[8:9] offset:64
	v_cvt_pk_bf16_f32 v154, v14, v15
	v_cvt_pk_bf16_f32 v155, v16, v17
	global_store_dwordx2 v132, v[154:155], s[6:7] offset:256
	global_store_dwordx4 v133, v[14:17], s[8:9] offset:512
	v_cvt_pk_bf16_f32 v156, v10, v11
	v_cvt_pk_bf16_f32 v157, v12, v13
	global_store_dwordx2 v132, v[156:157], s[6:7] offset:288
	global_store_dwordx4 v133, v[10:13], s[8:9] offset:576
	s_add_u32 s6, s6, s58
	s_addc_u32 s7, s7, 0
	s_add_u32 s8, s8, s70
	s_addc_u32 s9, s9, 0
	v_cvt_pk_bf16_f32 v158, v38, v39
	v_cvt_pk_bf16_f32 v159, v40, v41
	global_store_dwordx2 v132, v[158:159], s[6:7] offset:0
	global_store_dwordx4 v133, v[38:41], s[8:9] offset:0
	v_cvt_pk_bf16_f32 v160, v34, v35
	v_cvt_pk_bf16_f32 v161, v36, v37
	global_store_dwordx2 v132, v[160:161], s[6:7] offset:32
	global_store_dwordx4 v133, v[34:37], s[8:9] offset:64
	v_cvt_pk_bf16_f32 v162, v6, v7
	v_cvt_pk_bf16_f32 v163, v8, v9
	global_store_dwordx2 v132, v[162:163], s[6:7] offset:256
	global_store_dwordx4 v133, v[6:9], s[8:9] offset:512
	v_cvt_pk_bf16_f32 v164, v2, v3
	v_cvt_pk_bf16_f32 v165, v4, v5
	global_store_dwordx2 v132, v[164:165], s[6:7] offset:288
	global_store_dwordx4 v133, v[2:5], s[8:9] offset:576
	s_branch .LBB0_247
.Lkv_k_body_lat:
	v_lshlrev_b32_e32 v132, s84, v130
	v_lshl_add_u32 v132, v131, 1, v132
	s_lshl_b32 s58, 16, s84
	s_mul_i32 s59, s58, 5
	v_cvt_pk_bf16_f32 v134, v126, v127
	v_cvt_pk_bf16_f32 v135, v128, v129
	global_store_dwordx2 v132, v[134:135], s[6:7] offset:0
	v_cvt_pk_bf16_f32 v136, v122, v123
	v_cvt_pk_bf16_f32 v137, v124, v125
	global_store_dwordx2 v132, v[136:137], s[6:7] offset:32
	v_cvt_pk_bf16_f32 v138, v94, v95
	v_cvt_pk_bf16_f32 v139, v96, v97
	global_store_dwordx2 v132, v[138:139], s[6:7] offset:256
	v_cvt_pk_bf16_f32 v140, v90, v91
	v_cvt_pk_bf16_f32 v141, v92, v93
	global_store_dwordx2 v132, v[140:141], s[6:7] offset:288
	s_add_u32 s6, s6, s58
	s_addc_u32 s7, s7, 0
	v_cvt_pk_bf16_f32 v142, v118, v119
	v_cvt_pk_bf16_f32 v143, v120, v121
	global_store_dwordx2 v132, v[142:143], s[6:7] offset:0
	v_cvt_pk_bf16_f32 v144, v114, v115
	v_cvt_pk_bf16_f32 v145, v116, v117
	global_store_dwordx2 v132, v[144:145], s[6:7] offset:32
	v_cvt_pk_bf16_f32 v146, v86, v87
	v_cvt_pk_bf16_f32 v147, v88, v89
	global_store_dwordx2 v132, v[146:147], s[6:7] offset:256
	v_cvt_pk_bf16_f32 v148, v82, v83
	v_cvt_pk_bf16_f32 v149, v84, v85
	global_store_dwordx2 v132, v[148:149], s[6:7] offset:288
	s_add_u32 s6, s6, s58
	s_addc_u32 s7, s7, 0
	v_cvt_pk_bf16_f32 v150, v110, v111
	v_cvt_pk_bf16_f32 v151, v112, v113
	global_store_dwordx2 v132, v[150:151], s[6:7] offset:0
	v_cvt_pk_bf16_f32 v152, v106, v107
	v_cvt_pk_bf16_f32 v153, v108, v109
	global_store_dwordx2 v132, v[152:153], s[6:7] offset:32
	v_cvt_pk_bf16_f32 v154, v78, v79
	v_cvt_pk_bf16_f32 v155, v80, v81
	global_store_dwordx2 v132, v[154:155], s[6:7] offset:256
	v_cvt_pk_bf16_f32 v156, v74, v75
	v_cvt_pk_bf16_f32 v157, v76, v77
	global_store_dwordx2 v132, v[156:157], s[6:7] offset:288
	s_add_u32 s6, s6, s58
	s_addc_u32 s7, s7, 0
	v_cvt_pk_bf16_f32 v158, v102, v103
	v_cvt_pk_bf16_f32 v159, v104, v105
	global_store_dwordx2 v132, v[158:159], s[6:7] offset:0
	v_cvt_pk_bf16_f32 v160, v98, v99
	v_cvt_pk_bf16_f32 v161, v100, v101
	global_store_dwordx2 v132, v[160:161], s[6:7] offset:32
	v_cvt_pk_bf16_f32 v162, v70, v71
	v_cvt_pk_bf16_f32 v163, v72, v73
	global_store_dwordx2 v132, v[162:163], s[6:7] offset:256
	v_cvt_pk_bf16_f32 v164, v66, v67
	v_cvt_pk_bf16_f32 v165, v68, v69
	global_store_dwordx2 v132, v[164:165], s[6:7] offset:288
	s_add_u32 s6, s6, s59
	s_addc_u32 s7, s7, 0
	v_cvt_pk_bf16_f32 v134, v62, v63
	v_cvt_pk_bf16_f32 v135, v64, v65
	global_store_dwordx2 v132, v[134:135], s[6:7] offset:0
	v_cvt_pk_bf16_f32 v136, v58, v59
	v_cvt_pk_bf16_f32 v137, v60, v61
	global_store_dwordx2 v132, v[136:137], s[6:7] offset:32
	v_cvt_pk_bf16_f32 v138, v30, v31
	v_cvt_pk_bf16_f32 v139, v32, v33
	global_store_dwordx2 v132, v[138:139], s[6:7] offset:256
	v_cvt_pk_bf16_f32 v140, v26, v27
	v_cvt_pk_bf16_f32 v141, v28, v29
	global_store_dwordx2 v132, v[140:141], s[6:7] offset:288
	s_add_u32 s6, s6, s58
	s_addc_u32 s7, s7, 0
	v_cvt_pk_bf16_f32 v142, v54, v55
	v_cvt_pk_bf16_f32 v143, v56, v57
	global_store_dwordx2 v132, v[142:143], s[6:7] offset:0
	v_cvt_pk_bf16_f32 v144, v50, v51
	v_cvt_pk_bf16_f32 v145, v52, v53
	global_store_dwordx2 v132, v[144:145], s[6:7] offset:32
	v_cvt_pk_bf16_f32 v146, v22, v23
	v_cvt_pk_bf16_f32 v147, v24, v25
	global_store_dwordx2 v132, v[146:147], s[6:7] offset:256
	v_cvt_pk_bf16_f32 v148, v18, v19
	v_cvt_pk_bf16_f32 v149, v20, v21
	global_store_dwordx2 v132, v[148:149], s[6:7] offset:288
	s_add_u32 s6, s6, s58
	s_addc_u32 s7, s7, 0
	v_cvt_pk_bf16_f32 v150, v46, v47
	v_cvt_pk_bf16_f32 v151, v48, v49
	global_store_dwordx2 v132, v[150:151], s[6:7] offset:0
	v_cvt_pk_bf16_f32 v152, v42, v43
	v_cvt_pk_bf16_f32 v153, v44, v45
	global_store_dwordx2 v132, v[152:153], s[6:7] offset:32
	v_cvt_pk_bf16_f32 v154, v14, v15
	v_cvt_pk_bf16_f32 v155, v16, v17
	global_store_dwordx2 v132, v[154:155], s[6:7] offset:256
	v_cvt_pk_bf16_f32 v156, v10, v11
	v_cvt_pk_bf16_f32 v157, v12, v13
	global_store_dwordx2 v132, v[156:157], s[6:7] offset:288
	s_add_u32 s6, s6, s58
	s_addc_u32 s7, s7, 0
	v_cvt_pk_bf16_f32 v158, v38, v39
	v_cvt_pk_bf16_f32 v159, v40, v41
	global_store_dwordx2 v132, v[158:159], s[6:7] offset:0
	v_cvt_pk_bf16_f32 v160, v34, v35
	v_cvt_pk_bf16_f32 v161, v36, v37
	global_store_dwordx2 v132, v[160:161], s[6:7] offset:32
	v_cvt_pk_bf16_f32 v162, v6, v7
	v_cvt_pk_bf16_f32 v163, v8, v9
	global_store_dwordx2 v132, v[162:163], s[6:7] offset:256
	v_cvt_pk_bf16_f32 v164, v2, v3
	v_cvt_pk_bf16_f32 v165, v4, v5
	global_store_dwordx2 v132, v[164:165], s[6:7] offset:288
	s_branch .LBB0_247
.Lkv_v_body_ctx:
	v_mul_u32_u24_e32 v132, s76, v131
	v_lshl_add_u32 v132, v130, 1, v132
	s_mul_i32 s77, s76, 13
	s_mul_i32 s60, s76, 109
	v_cvt_pk_bf16_f32 v134, v126, v127
	v_cvt_pk_bf16_f32 v135, v128, v129
	v_cvt_pk_bf16_f32 v136, v118, v119
	v_cvt_pk_bf16_f32 v137, v120, v121
	v_cvt_pk_bf16_f32 v138, v110, v111
	v_cvt_pk_bf16_f32 v139, v112, v113
	v_cvt_pk_bf16_f32 v140, v102, v103
	v_cvt_pk_bf16_f32 v141, v104, v105
	v_cvt_pk_bf16_f32 v142, v62, v63
	v_cvt_pk_bf16_f32 v143, v64, v65
	v_cvt_pk_bf16_f32 v144, v54, v55
	v_cvt_pk_bf16_f32 v145, v56, v57
	v_cvt_pk_bf16_f32 v146, v46, v47
	v_cvt_pk_bf16_f32 v147, v48, v49
	v_cvt_pk_bf16_f32 v148, v38, v39
	v_cvt_pk_bf16_f32 v149, v40, v41
	global_store_short v132, v134, s[6:7] offset:0
	global_store_short v132, v136, s[6:7] offset:32
	global_store_short v132, v138, s[6:7] offset:64
	global_store_short v132, v140, s[6:7] offset:96
	global_store_short v132, v142, s[6:7] offset:256
	global_store_short v132, v144, s[6:7] offset:288
	global_store_short v132, v146, s[6:7] offset:320
	global_store_short v132, v148, s[6:7] offset:352
	s_add_u32 s6, s6, s76
	s_addc_u32 s7, s7, 0
	global_store_short_d16_hi v132, v134, s[6:7] offset:0
	global_store_short_d16_hi v132, v136, s[6:7] offset:32
	global_store_short_d16_hi v132, v138, s[6:7] offset:64
	global_store_short_d16_hi v132, v140, s[6:7] offset:96
	global_store_short_d16_hi v132, v142, s[6:7] offset:256
	global_store_short_d16_hi v132, v144, s[6:7] offset:288
	global_store_short_d16_hi v132, v146, s[6:7] offset:320
	global_store_short_d16_hi v132, v148, s[6:7] offset:352
	s_add_u32 s6, s6, s76
	s_addc_u32 s7, s7, 0
	global_store_short v132, v135, s[6:7] offset:0
	global_store_short v132, v137, s[6:7] offset:32
	global_store_short v132, v139, s[6:7] offset:64
	global_store_short v132, v141, s[6:7] offset:96
	global_store_short v132, v143, s[6:7] offset:256
	global_store_short v132, v145, s[6:7] offset:288
	global_store_short v132, v147, s[6:7] offset:320
	global_store_short v132, v149, s[6:7] offset:352
	s_add_u32 s6, s6, s76
	s_addc_u32 s7, s7, 0
	global_store_short_d16_hi v132, v135, s[6:7] offset:0
	global_store_short_d16_hi v132, v137, s[6:7] offset:32
	global_store_short_d16_hi v132, v139, s[6:7] offset:64
	global_store_short_d16_hi v132, v141, s[6:7] offset:96
	global_store_short_d16_hi v132, v143, s[6:7] offset:256
	global_store_short_d16_hi v132, v145, s[6:7] offset:288
	global_store_short_d16_hi v132, v147, s[6:7] offset:320
	global_store_short_d16_hi v132, v149, s[6:7] offset:352
	s_add_u32 s6, s6, s77
	s_addc_u32 s7, s7, 0
	v_cvt_pk_bf16_f32 v150, v122, v123
	v_cvt_pk_bf16_f32 v151, v124, v125
	v_cvt_pk_bf16_f32 v152, v114, v115
	v_cvt_pk_bf16_f32 v153, v116, v117
	v_cvt_pk_bf16_f32 v154, v106, v107
	v_cvt_pk_bf16_f32 v155, v108, v109
	v_cvt_pk_bf16_f32 v156, v98, v99
	v_cvt_pk_bf16_f32 v157, v100, v101
	v_cvt_pk_bf16_f32 v158, v58, v59
	v_cvt_pk_bf16_f32 v159, v60, v61
	v_cvt_pk_bf16_f32 v160, v50, v51
	v_cvt_pk_bf16_f32 v161, v52, v53
	v_cvt_pk_bf16_f32 v162, v42, v43
	v_cvt_pk_bf16_f32 v163, v44, v45
	v_cvt_pk_bf16_f32 v164, v34, v35
	v_cvt_pk_bf16_f32 v165, v36, v37
	global_store_short v132, v150, s[6:7] offset:0
	global_store_short v132, v152, s[6:7] offset:32
	global_store_short v132, v154, s[6:7] offset:64
	global_store_short v132, v156, s[6:7] offset:96
	global_store_short v132, v158, s[6:7] offset:256
	global_store_short v132, v160, s[6:7] offset:288
	global_store_short v132, v162, s[6:7] offset:320
	global_store_short v132, v164, s[6:7] offset:352
	s_add_u32 s6, s6, s76
	s_addc_u32 s7, s7, 0
	global_store_short_d16_hi v132, v150, s[6:7] offset:0
	global_store_short_d16_hi v132, v152, s[6:7] offset:32
	global_store_short_d16_hi v132, v154, s[6:7] offset:64
	global_store_short_d16_hi v132, v156, s[6:7] offset:96
	global_store_short_d16_hi v132, v158, s[6:7] offset:256
	global_store_short_d16_hi v132, v160, s[6:7] offset:288
	global_store_short_d16_hi v132, v162, s[6:7] offset:320
	global_store_short_d16_hi v132, v164, s[6:7] offset:352
	s_add_u32 s6, s6, s76
	s_addc_u32 s7, s7, 0
	global_store_short v132, v151, s[6:7] offset:0
	global_store_short v132, v153, s[6:7] offset:32
	global_store_short v132, v155, s[6:7] offset:64
	global_store_short v132, v157, s[6:7] offset:96
	global_store_short v132, v159, s[6:7] offset:256
	global_store_short v132, v161, s[6:7] offset:288
	global_store_short v132, v163, s[6:7] offset:320
	global_store_short v132, v165, s[6:7] offset:352
	s_add_u32 s6, s6, s76
	s_addc_u32 s7, s7, 0
	global_store_short_d16_hi v132, v151, s[6:7] offset:0
	global_store_short_d16_hi v132, v153, s[6:7] offset:32
	global_store_short_d16_hi v132, v155, s[6:7] offset:64
	global_store_short_d16_hi v132, v157, s[6:7] offset:96
	global_store_short_d16_hi v132, v159, s[6:7] offset:256
	global_store_short_d16_hi v132, v161, s[6:7] offset:288
	global_store_short_d16_hi v132, v163, s[6:7] offset:320
	global_store_short_d16_hi v132, v165, s[6:7] offset:352
	s_add_u32 s6, s6, s60
	s_addc_u32 s7, s7, 0
	v_cvt_pk_bf16_f32 v134, v94, v95
	v_cvt_pk_bf16_f32 v135, v96, v97
	v_cvt_pk_bf16_f32 v136, v86, v87
	v_cvt_pk_bf16_f32 v137, v88, v89
	v_cvt_pk_bf16_f32 v138, v78, v79
	v_cvt_pk_bf16_f32 v139, v80, v81
	v_cvt_pk_bf16_f32 v140, v70, v71
	v_cvt_pk_bf16_f32 v141, v72, v73
	v_cvt_pk_bf16_f32 v142, v30, v31
	v_cvt_pk_bf16_f32 v143, v32, v33
	v_cvt_pk_bf16_f32 v144, v22, v23
	v_cvt_pk_bf16_f32 v145, v24, v25
	v_cvt_pk_bf16_f32 v146, v14, v15
	v_cvt_pk_bf16_f32 v147, v16, v17
	v_cvt_pk_bf16_f32 v148, v6, v7
	v_cvt_pk_bf16_f32 v149, v8, v9
	global_store_short v132, v134, s[6:7] offset:0
	global_store_short v132, v136, s[6:7] offset:32
	global_store_short v132, v138, s[6:7] offset:64
	global_store_short v132, v140, s[6:7] offset:96
	global_store_short v132, v142, s[6:7] offset:256
	global_store_short v132, v144, s[6:7] offset:288
	global_store_short v132, v146, s[6:7] offset:320
	global_store_short v132, v148, s[6:7] offset:352
	s_add_u32 s6, s6, s76
	s_addc_u32 s7, s7, 0
	global_store_short_d16_hi v132, v134, s[6:7] offset:0
	global_store_short_d16_hi v132, v136, s[6:7] offset:32
	global_store_short_d16_hi v132, v138, s[6:7] offset:64
	global_store_short_d16_hi v132, v140, s[6:7] offset:96
	global_store_short_d16_hi v132, v142, s[6:7] offset:256
	global_store_short_d16_hi v132, v144, s[6:7] offset:288
	global_store_short_d16_hi v132, v146, s[6:7] offset:320
	global_store_short_d16_hi v132, v148, s[6:7] offset:352
	s_add_u32 s6, s6, s76
	s_addc_u32 s7, s7, 0
	global_store_short v132, v135, s[6:7] offset:0
	global_store_short v132, v137, s[6:7] offset:32
	global_store_short v132, v139, s[6:7] offset:64
	global_store_short v132, v141, s[6:7] offset:96
	global_store_short v132, v143, s[6:7] offset:256
	global_store_short v132, v145, s[6:7] offset:288
	global_store_short v132, v147, s[6:7] offset:320
	global_store_short v132, v149, s[6:7] offset:352
	s_add_u32 s6, s6, s76
	s_addc_u32 s7, s7, 0
	global_store_short_d16_hi v132, v135, s[6:7] offset:0
	global_store_short_d16_hi v132, v137, s[6:7] offset:32
	global_store_short_d16_hi v132, v139, s[6:7] offset:64
	global_store_short_d16_hi v132, v141, s[6:7] offset:96
	global_store_short_d16_hi v132, v143, s[6:7] offset:256
	global_store_short_d16_hi v132, v145, s[6:7] offset:288
	global_store_short_d16_hi v132, v147, s[6:7] offset:320
	global_store_short_d16_hi v132, v149, s[6:7] offset:352
	s_add_u32 s6, s6, s77
	s_addc_u32 s7, s7, 0
	v_cvt_pk_bf16_f32 v150, v90, v91
	v_cvt_pk_bf16_f32 v151, v92, v93
	v_cvt_pk_bf16_f32 v152, v82, v83
	v_cvt_pk_bf16_f32 v153, v84, v85
	v_cvt_pk_bf16_f32 v154, v74, v75
	v_cvt_pk_bf16_f32 v155, v76, v77
	v_cvt_pk_bf16_f32 v156, v66, v67
	v_cvt_pk_bf16_f32 v157, v68, v69
	v_cvt_pk_bf16_f32 v158, v26, v27
	v_cvt_pk_bf16_f32 v159, v28, v29
	v_cvt_pk_bf16_f32 v160, v18, v19
	v_cvt_pk_bf16_f32 v161, v20, v21
	v_cvt_pk_bf16_f32 v162, v10, v11
	v_cvt_pk_bf16_f32 v163, v12, v13
	v_cvt_pk_bf16_f32 v164, v2, v3
	v_cvt_pk_bf16_f32 v165, v4, v5
	global_store_short v132, v150, s[6:7] offset:0
	global_store_short v132, v152, s[6:7] offset:32
	global_store_short v132, v154, s[6:7] offset:64
	global_store_short v132, v156, s[6:7] offset:96
	global_store_short v132, v158, s[6:7] offset:256
	global_store_short v132, v160, s[6:7] offset:288
	global_store_short v132, v162, s[6:7] offset:320
	global_store_short v132, v164, s[6:7] offset:352
	s_add_u32 s6, s6, s76
	s_addc_u32 s7, s7, 0
	global_store_short_d16_hi v132, v150, s[6:7] offset:0
	global_store_short_d16_hi v132, v152, s[6:7] offset:32
	global_store_short_d16_hi v132, v154, s[6:7] offset:64
	global_store_short_d16_hi v132, v156, s[6:7] offset:96
	global_store_short_d16_hi v132, v158, s[6:7] offset:256
	global_store_short_d16_hi v132, v160, s[6:7] offset:288
	global_store_short_d16_hi v132, v162, s[6:7] offset:320
	global_store_short_d16_hi v132, v164, s[6:7] offset:352
	s_add_u32 s6, s6, s76
	s_addc_u32 s7, s7, 0
	global_store_short v132, v151, s[6:7] offset:0
	global_store_short v132, v153, s[6:7] offset:32
	global_store_short v132, v155, s[6:7] offset:64
	global_store_short v132, v157, s[6:7] offset:96
	global_store_short v132, v159, s[6:7] offset:256
	global_store_short v132, v161, s[6:7] offset:288
	global_store_short v132, v163, s[6:7] offset:320
	global_store_short v132, v165, s[6:7] offset:352
	s_add_u32 s6, s6, s76
	s_addc_u32 s7, s7, 0
	global_store_short_d16_hi v132, v151, s[6:7] offset:0
	global_store_short_d16_hi v132, v153, s[6:7] offset:32
	global_store_short_d16_hi v132, v155, s[6:7] offset:64
	global_store_short_d16_hi v132, v157, s[6:7] offset:96
	global_store_short_d16_hi v132, v159, s[6:7] offset:256
	global_store_short_d16_hi v132, v161, s[6:7] offset:288
	global_store_short_d16_hi v132, v163, s[6:7] offset:320
	global_store_short_d16_hi v132, v165, s[6:7] offset:352
	global_store_dwordx4 v133, v[126:129], s[8:9] offset:0
	global_store_dwordx4 v133, v[122:125], s[8:9] offset:64
	global_store_dwordx4 v133, v[94:97], s[8:9] offset:512
	global_store_dwordx4 v133, v[90:93], s[8:9] offset:576
	s_add_u32 s8, s8, s70
	s_addc_u32 s9, s9, 0
	global_store_dwordx4 v133, v[118:121], s[8:9] offset:0
	global_store_dwordx4 v133, v[114:117], s[8:9] offset:64
	global_store_dwordx4 v133, v[86:89], s[8:9] offset:512
	global_store_dwordx4 v133, v[82:85], s[8:9] offset:576
	s_add_u32 s8, s8, s70
	s_addc_u32 s9, s9, 0
	global_store_dwordx4 v133, v[110:113], s[8:9] offset:0
	global_store_dwordx4 v133, v[106:109], s[8:9] offset:64
	global_store_dwordx4 v133, v[78:81], s[8:9] offset:512
	global_store_dwordx4 v133, v[74:77], s[8:9] offset:576
	s_add_u32 s8, s8, s70
	s_addc_u32 s9, s9, 0
	global_store_dwordx4 v133, v[102:105], s[8:9] offset:0
	global_store_dwordx4 v133, v[98:101], s[8:9] offset:64
	global_store_dwordx4 v133, v[70:73], s[8:9] offset:512
	global_store_dwordx4 v133, v[66:69], s[8:9] offset:576
	s_add_u32 s8, s8, s71
	s_addc_u32 s9, s9, 0
	global_store_dwordx4 v133, v[62:65], s[8:9] offset:0
	global_store_dwordx4 v133, v[58:61], s[8:9] offset:64
	global_store_dwordx4 v133, v[30:33], s[8:9] offset:512
	global_store_dwordx4 v133, v[26:29], s[8:9] offset:576
	s_add_u32 s8, s8, s70
	s_addc_u32 s9, s9, 0
	global_store_dwordx4 v133, v[54:57], s[8:9] offset:0
	global_store_dwordx4 v133, v[50:53], s[8:9] offset:64
	global_store_dwordx4 v133, v[22:25], s[8:9] offset:512
	global_store_dwordx4 v133, v[18:21], s[8:9] offset:576
	s_add_u32 s8, s8, s70
	s_addc_u32 s9, s9, 0
	global_store_dwordx4 v133, v[46:49], s[8:9] offset:0
	global_store_dwordx4 v133, v[42:45], s[8:9] offset:64
	global_store_dwordx4 v133, v[14:17], s[8:9] offset:512
	global_store_dwordx4 v133, v[10:13], s[8:9] offset:576
	s_add_u32 s8, s8, s70
	s_addc_u32 s9, s9, 0
	global_store_dwordx4 v133, v[38:41], s[8:9] offset:0
	global_store_dwordx4 v133, v[34:37], s[8:9] offset:64
	global_store_dwordx4 v133, v[6:9], s[8:9] offset:512
	global_store_dwordx4 v133, v[2:5], s[8:9] offset:576
	s_branch .LBB0_247
.Lkv_v_body_lat:
	v_mul_u32_u24_e32 v132, s76, v131
	v_lshl_add_u32 v132, v130, 1, v132
	s_mul_i32 s77, s76, 13
	s_mul_i32 s60, s76, 109
	v_cvt_pk_bf16_f32 v134, v126, v127
	v_cvt_pk_bf16_f32 v135, v128, v129
	v_cvt_pk_bf16_f32 v136, v118, v119
	v_cvt_pk_bf16_f32 v137, v120, v121
	v_cvt_pk_bf16_f32 v138, v110, v111
	v_cvt_pk_bf16_f32 v139, v112, v113
	v_cvt_pk_bf16_f32 v140, v102, v103
	v_cvt_pk_bf16_f32 v141, v104, v105
	v_cvt_pk_bf16_f32 v142, v62, v63
	v_cvt_pk_bf16_f32 v143, v64, v65
	v_cvt_pk_bf16_f32 v144, v54, v55
	v_cvt_pk_bf16_f32 v145, v56, v57
	v_cvt_pk_bf16_f32 v146, v46, v47
	v_cvt_pk_bf16_f32 v147, v48, v49
	v_cvt_pk_bf16_f32 v148, v38, v39
	v_cvt_pk_bf16_f32 v149, v40, v41
	global_store_short v132, v134, s[6:7] offset:0
	global_store_short v132, v136, s[6:7] offset:32
	global_store_short v132, v138, s[6:7] offset:64
	global_store_short v132, v140, s[6:7] offset:96
	global_store_short v132, v142, s[6:7] offset:256
	global_store_short v132, v144, s[6:7] offset:288
	global_store_short v132, v146, s[6:7] offset:320
	global_store_short v132, v148, s[6:7] offset:352
	s_add_u32 s6, s6, s76
	s_addc_u32 s7, s7, 0
	global_store_short_d16_hi v132, v134, s[6:7] offset:0
	global_store_short_d16_hi v132, v136, s[6:7] offset:32
	global_store_short_d16_hi v132, v138, s[6:7] offset:64
	global_store_short_d16_hi v132, v140, s[6:7] offset:96
	global_store_short_d16_hi v132, v142, s[6:7] offset:256
	global_store_short_d16_hi v132, v144, s[6:7] offset:288
	global_store_short_d16_hi v132, v146, s[6:7] offset:320
	global_store_short_d16_hi v132, v148, s[6:7] offset:352
	s_add_u32 s6, s6, s76
	s_addc_u32 s7, s7, 0
	global_store_short v132, v135, s[6:7] offset:0
	global_store_short v132, v137, s[6:7] offset:32
	global_store_short v132, v139, s[6:7] offset:64
	global_store_short v132, v141, s[6:7] offset:96
	global_store_short v132, v143, s[6:7] offset:256
	global_store_short v132, v145, s[6:7] offset:288
	global_store_short v132, v147, s[6:7] offset:320
	global_store_short v132, v149, s[6:7] offset:352
	s_add_u32 s6, s6, s76
	s_addc_u32 s7, s7, 0
	global_store_short_d16_hi v132, v135, s[6:7] offset:0
	global_store_short_d16_hi v132, v137, s[6:7] offset:32
	global_store_short_d16_hi v132, v139, s[6:7] offset:64
	global_store_short_d16_hi v132, v141, s[6:7] offset:96
	global_store_short_d16_hi v132, v143, s[6:7] offset:256
	global_store_short_d16_hi v132, v145, s[6:7] offset:288
	global_store_short_d16_hi v132, v147, s[6:7] offset:320
	global_store_short_d16_hi v132, v149, s[6:7] offset:352
	s_add_u32 s6, s6, s77
	s_addc_u32 s7, s7, 0
	v_cvt_pk_bf16_f32 v150, v122, v123
	v_cvt_pk_bf16_f32 v151, v124, v125
	v_cvt_pk_bf16_f32 v152, v114, v115
	v_cvt_pk_bf16_f32 v153, v116, v117
	v_cvt_pk_bf16_f32 v154, v106, v107
	v_cvt_pk_bf16_f32 v155, v108, v109
	v_cvt_pk_bf16_f32 v156, v98, v99
	v_cvt_pk_bf16_f32 v157, v100, v101
	v_cvt_pk_bf16_f32 v158, v58, v59
	v_cvt_pk_bf16_f32 v159, v60, v61
	v_cvt_pk_bf16_f32 v160, v50, v51
	v_cvt_pk_bf16_f32 v161, v52, v53
	v_cvt_pk_bf16_f32 v162, v42, v43
	v_cvt_pk_bf16_f32 v163, v44, v45
	v_cvt_pk_bf16_f32 v164, v34, v35
	v_cvt_pk_bf16_f32 v165, v36, v37
	global_store_short v132, v150, s[6:7] offset:0
	global_store_short v132, v152, s[6:7] offset:32
	global_store_short v132, v154, s[6:7] offset:64
	global_store_short v132, v156, s[6:7] offset:96
	global_store_short v132, v158, s[6:7] offset:256
	global_store_short v132, v160, s[6:7] offset:288
	global_store_short v132, v162, s[6:7] offset:320
	global_store_short v132, v164, s[6:7] offset:352
	s_add_u32 s6, s6, s76
	s_addc_u32 s7, s7, 0
	global_store_short_d16_hi v132, v150, s[6:7] offset:0
	global_store_short_d16_hi v132, v152, s[6:7] offset:32
	global_store_short_d16_hi v132, v154, s[6:7] offset:64
	global_store_short_d16_hi v132, v156, s[6:7] offset:96
	global_store_short_d16_hi v132, v158, s[6:7] offset:256
	global_store_short_d16_hi v132, v160, s[6:7] offset:288
	global_store_short_d16_hi v132, v162, s[6:7] offset:320
	global_store_short_d16_hi v132, v164, s[6:7] offset:352
	s_add_u32 s6, s6, s76
	s_addc_u32 s7, s7, 0
	global_store_short v132, v151, s[6:7] offset:0
	global_store_short v132, v153, s[6:7] offset:32
	global_store_short v132, v155, s[6:7] offset:64
	global_store_short v132, v157, s[6:7] offset:96
	global_store_short v132, v159, s[6:7] offset:256
	global_store_short v132, v161, s[6:7] offset:288
	global_store_short v132, v163, s[6:7] offset:320
	global_store_short v132, v165, s[6:7] offset:352
	s_add_u32 s6, s6, s76
	s_addc_u32 s7, s7, 0
	global_store_short_d16_hi v132, v151, s[6:7] offset:0
	global_store_short_d16_hi v132, v153, s[6:7] offset:32
	global_store_short_d16_hi v132, v155, s[6:7] offset:64
	global_store_short_d16_hi v132, v157, s[6:7] offset:96
	global_store_short_d16_hi v132, v159, s[6:7] offset:256
	global_store_short_d16_hi v132, v161, s[6:7] offset:288
	global_store_short_d16_hi v132, v163, s[6:7] offset:320
	global_store_short_d16_hi v132, v165, s[6:7] offset:352
	s_add_u32 s6, s6, s60
	s_addc_u32 s7, s7, 0
	v_cvt_pk_bf16_f32 v134, v94, v95
	v_cvt_pk_bf16_f32 v135, v96, v97
	v_cvt_pk_bf16_f32 v136, v86, v87
	v_cvt_pk_bf16_f32 v137, v88, v89
	v_cvt_pk_bf16_f32 v138, v78, v79
	v_cvt_pk_bf16_f32 v139, v80, v81
	v_cvt_pk_bf16_f32 v140, v70, v71
	v_cvt_pk_bf16_f32 v141, v72, v73
	v_cvt_pk_bf16_f32 v142, v30, v31
	v_cvt_pk_bf16_f32 v143, v32, v33
	v_cvt_pk_bf16_f32 v144, v22, v23
	v_cvt_pk_bf16_f32 v145, v24, v25
	v_cvt_pk_bf16_f32 v146, v14, v15
	v_cvt_pk_bf16_f32 v147, v16, v17
	v_cvt_pk_bf16_f32 v148, v6, v7
	v_cvt_pk_bf16_f32 v149, v8, v9
	global_store_short v132, v134, s[6:7] offset:0
	global_store_short v132, v136, s[6:7] offset:32
	global_store_short v132, v138, s[6:7] offset:64
	global_store_short v132, v140, s[6:7] offset:96
	global_store_short v132, v142, s[6:7] offset:256
	global_store_short v132, v144, s[6:7] offset:288
	global_store_short v132, v146, s[6:7] offset:320
	global_store_short v132, v148, s[6:7] offset:352
	s_add_u32 s6, s6, s76
	s_addc_u32 s7, s7, 0
	global_store_short_d16_hi v132, v134, s[6:7] offset:0
	global_store_short_d16_hi v132, v136, s[6:7] offset:32
	global_store_short_d16_hi v132, v138, s[6:7] offset:64
	global_store_short_d16_hi v132, v140, s[6:7] offset:96
	global_store_short_d16_hi v132, v142, s[6:7] offset:256
	global_store_short_d16_hi v132, v144, s[6:7] offset:288
	global_store_short_d16_hi v132, v146, s[6:7] offset:320
	global_store_short_d16_hi v132, v148, s[6:7] offset:352
	s_add_u32 s6, s6, s76
	s_addc_u32 s7, s7, 0
	global_store_short v132, v135, s[6:7] offset:0
	global_store_short v132, v137, s[6:7] offset:32
	global_store_short v132, v139, s[6:7] offset:64
	global_store_short v132, v141, s[6:7] offset:96
	global_store_short v132, v143, s[6:7] offset:256
	global_store_short v132, v145, s[6:7] offset:288
	global_store_short v132, v147, s[6:7] offset:320
	global_store_short v132, v149, s[6:7] offset:352
	s_add_u32 s6, s6, s76
	s_addc_u32 s7, s7, 0
	global_store_short_d16_hi v132, v135, s[6:7] offset:0
	global_store_short_d16_hi v132, v137, s[6:7] offset:32
	global_store_short_d16_hi v132, v139, s[6:7] offset:64
	global_store_short_d16_hi v132, v141, s[6:7] offset:96
	global_store_short_d16_hi v132, v143, s[6:7] offset:256
	global_store_short_d16_hi v132, v145, s[6:7] offset:288
	global_store_short_d16_hi v132, v147, s[6:7] offset:320
	global_store_short_d16_hi v132, v149, s[6:7] offset:352
	s_add_u32 s6, s6, s77
	s_addc_u32 s7, s7, 0
	v_cvt_pk_bf16_f32 v150, v90, v91
	v_cvt_pk_bf16_f32 v151, v92, v93
	v_cvt_pk_bf16_f32 v152, v82, v83
	v_cvt_pk_bf16_f32 v153, v84, v85
	v_cvt_pk_bf16_f32 v154, v74, v75
	v_cvt_pk_bf16_f32 v155, v76, v77
	v_cvt_pk_bf16_f32 v156, v66, v67
	v_cvt_pk_bf16_f32 v157, v68, v69
	v_cvt_pk_bf16_f32 v158, v26, v27
	v_cvt_pk_bf16_f32 v159, v28, v29
	v_cvt_pk_bf16_f32 v160, v18, v19
	v_cvt_pk_bf16_f32 v161, v20, v21
	v_cvt_pk_bf16_f32 v162, v10, v11
	v_cvt_pk_bf16_f32 v163, v12, v13
	v_cvt_pk_bf16_f32 v164, v2, v3
	v_cvt_pk_bf16_f32 v165, v4, v5
	global_store_short v132, v150, s[6:7] offset:0
	global_store_short v132, v152, s[6:7] offset:32
	global_store_short v132, v154, s[6:7] offset:64
	global_store_short v132, v156, s[6:7] offset:96
	global_store_short v132, v158, s[6:7] offset:256
	global_store_short v132, v160, s[6:7] offset:288
	global_store_short v132, v162, s[6:7] offset:320
	global_store_short v132, v164, s[6:7] offset:352
	s_add_u32 s6, s6, s76
	s_addc_u32 s7, s7, 0
	global_store_short_d16_hi v132, v150, s[6:7] offset:0
	global_store_short_d16_hi v132, v152, s[6:7] offset:32
	global_store_short_d16_hi v132, v154, s[6:7] offset:64
	global_store_short_d16_hi v132, v156, s[6:7] offset:96
	global_store_short_d16_hi v132, v158, s[6:7] offset:256
	global_store_short_d16_hi v132, v160, s[6:7] offset:288
	global_store_short_d16_hi v132, v162, s[6:7] offset:320
	global_store_short_d16_hi v132, v164, s[6:7] offset:352
	s_add_u32 s6, s6, s76
	s_addc_u32 s7, s7, 0
	global_store_short v132, v151, s[6:7] offset:0
	global_store_short v132, v153, s[6:7] offset:32
	global_store_short v132, v155, s[6:7] offset:64
	global_store_short v132, v157, s[6:7] offset:96
	global_store_short v132, v159, s[6:7] offset:256
	global_store_short v132, v161, s[6:7] offset:288
	global_store_short v132, v163, s[6:7] offset:320
	global_store_short v132, v165, s[6:7] offset:352
	s_add_u32 s6, s6, s76
	s_addc_u32 s7, s7, 0
	global_store_short_d16_hi v132, v151, s[6:7] offset:0
	global_store_short_d16_hi v132, v153, s[6:7] offset:32
	global_store_short_d16_hi v132, v155, s[6:7] offset:64
	global_store_short_d16_hi v132, v157, s[6:7] offset:96
	global_store_short_d16_hi v132, v159, s[6:7] offset:256
	global_store_short_d16_hi v132, v161, s[6:7] offset:288
	global_store_short_d16_hi v132, v163, s[6:7] offset:320
	global_store_short_d16_hi v132, v165, s[6:7] offset:352
	s_branch .LBB0_247
